# adds compress-GEMM epilogue through an LDS transpose (16 full-row dwordx4 stores instead of 32 partial dwordx2); init-quad wait states by reordering instead of a pad
# baseline (speedup 1.0000x reference)
; __device__ __forceinline__ unsigned cvt_pk_bf16(float lo, float hi) { typedef float f2_ __attribute__((ext_vector_type(2))); typedef __bf16 b2_ __attribute__((ext_vector_type(2))); f2_ v = {lo, hi}; b2_ b = __builtin_convertvector(v, b2_); return __builtin_bit_cast(unsigned, b); }
; template <class Tp> DEV Tp* wsp(const Frame& F, size_t off) { return (Tp*)(F.ws + off); }
; DEV void cmp_gemm_unit(Frame& F, int ty, int pm) {
;     ...
;     bf16* Tm = wsp<bf16>(F, ty ? WS_TV : WS_TK);
; #pragma unroll
;     for (int mt = 0; mt < 2; ++mt) { bf16* tp = Tm + (size_t)(pm * 256 + 32 * w + 16 * mt + n) * 256 + 4 * q4;
; #pragma unroll
;         for (int nt = 0; nt < 16; ++nt) { v2u wv; wv.x = pg8::cvt_pk_bf16(acc[mt][nt][0], acc[mt][nt][1]); wv.y = pg8::cvt_pk_bf16(acc[mt][nt][2], acc[mt][nt][3]); *(v2u*)(tp + 16 * nt) = wv; } }
;     __syncthreads();
.LBB0_653:
	s_and_b64 s[6:7], s[6:7], exec
	s_cselect_b32 s0, s15, 0x22900000
	s_add_u32 s6, s72, s0
	s_addc_u32 s7, s73, 0
	s_lshl_b32 s8, s16, 9
	s_add_u32 s6, s6, s8
	s_addc_u32 s7, s7, 0
	s_mul_i32 s9, s13, 528
	v_mul_u32_u24_e32 v10, 528, v224
	v_lshl_add_u32 v10, v211, 3, v10
	v_add_u32_e32 v10, s9, v10
	v_lshrrev_b32_e32 v11, 5, v210
	v_and_b32_e32 v12, 31, v210
	v_mul_u32_u24_e32 v13, 528, v11
	v_lshl_add_u32 v13, v12, 4, v13
	v_add_u32_e32 v13, s9, v13
	v_lshlrev_b32_e32 v11, 9, v11
	v_lshl_add_u32 v11, v12, 4, v11
	v_cvt_pk_bf16_f32 v2, v102, v103
	v_cvt_pk_bf16_f32 v3, v104, v105
	ds_write_b64 v10, v[2:3] offset:0
	v_cvt_pk_bf16_f32 v4, v50, v51
	v_cvt_pk_bf16_f32 v5, v52, v53
	ds_write_b64 v10, v[4:5] offset:8448
	v_cvt_pk_bf16_f32 v6, v118, v119
	v_cvt_pk_bf16_f32 v7, v120, v121
	ds_write_b64 v10, v[6:7] offset:32
	v_cvt_pk_bf16_f32 v8, v54, v55
	v_cvt_pk_bf16_f32 v9, v56, v57
	ds_write_b64 v10, v[8:9] offset:8480
	v_cvt_pk_bf16_f32 v2, v122, v123
	v_cvt_pk_bf16_f32 v3, v124, v125
	ds_write_b64 v10, v[2:3] offset:64
	v_cvt_pk_bf16_f32 v4, v58, v59
	v_cvt_pk_bf16_f32 v5, v60, v61
	ds_write_b64 v10, v[4:5] offset:8512
	v_cvt_pk_bf16_f32 v6, v126, v127
	v_cvt_pk_bf16_f32 v7, v128, v129
	ds_write_b64 v10, v[6:7] offset:96
	v_cvt_pk_bf16_f32 v8, v62, v63
	v_cvt_pk_bf16_f32 v9, v64, v65
	ds_write_b64 v10, v[8:9] offset:8544
	v_cvt_pk_bf16_f32 v2, v130, v131
	v_cvt_pk_bf16_f32 v3, v132, v133
	ds_write_b64 v10, v[2:3] offset:128
	v_cvt_pk_bf16_f32 v4, v18, v19
	v_cvt_pk_bf16_f32 v5, v20, v21
	ds_write_b64 v10, v[4:5] offset:8576
	v_cvt_pk_bf16_f32 v6, v134, v135
	v_cvt_pk_bf16_f32 v7, v136, v137
	ds_write_b64 v10, v[6:7] offset:160
	v_cvt_pk_bf16_f32 v8, v22, v23
	v_cvt_pk_bf16_f32 v9, v24, v25
	ds_write_b64 v10, v[8:9] offset:8608
	v_cvt_pk_bf16_f32 v2, v138, v139
	v_cvt_pk_bf16_f32 v3, v140, v141
	ds_write_b64 v10, v[2:3] offset:192
	v_cvt_pk_bf16_f32 v4, v26, v27
	v_cvt_pk_bf16_f32 v5, v28, v29
	ds_write_b64 v10, v[4:5] offset:8640
	v_cvt_pk_bf16_f32 v6, v142, v143
	v_cvt_pk_bf16_f32 v7, v144, v145
	ds_write_b64 v10, v[6:7] offset:224
	v_cvt_pk_bf16_f32 v8, v30, v31
	v_cvt_pk_bf16_f32 v9, v32, v33
	ds_write_b64 v10, v[8:9] offset:8672
	v_cvt_pk_bf16_f32 v2, v146, v147
	v_cvt_pk_bf16_f32 v3, v148, v149
	ds_write_b64 v10, v[2:3] offset:256
	v_cvt_pk_bf16_f32 v4, v34, v35
	v_cvt_pk_bf16_f32 v5, v36, v37
	ds_write_b64 v10, v[4:5] offset:8704
	v_cvt_pk_bf16_f32 v6, v150, v151
	v_cvt_pk_bf16_f32 v7, v152, v153
	ds_write_b64 v10, v[6:7] offset:288
	v_cvt_pk_bf16_f32 v8, v38, v39
	v_cvt_pk_bf16_f32 v9, v40, v41
	ds_write_b64 v10, v[8:9] offset:8736
	v_cvt_pk_bf16_f32 v2, v154, v155
	v_cvt_pk_bf16_f32 v3, v156, v157
	ds_write_b64 v10, v[2:3] offset:320
	v_cvt_pk_bf16_f32 v4, v42, v43
	v_cvt_pk_bf16_f32 v5, v44, v45
	ds_write_b64 v10, v[4:5] offset:8768
	v_cvt_pk_bf16_f32 v6, v158, v159
	v_cvt_pk_bf16_f32 v7, v160, v161
	ds_write_b64 v10, v[6:7] offset:352
	v_cvt_pk_bf16_f32 v8, v46, v47
	v_cvt_pk_bf16_f32 v9, v48, v49
	ds_write_b64 v10, v[8:9] offset:8800
	v_cvt_pk_bf16_f32 v2, v162, v163
	v_cvt_pk_bf16_f32 v3, v164, v165
	ds_write_b64 v10, v[2:3] offset:384
	v_cvt_pk_bf16_f32 v4, v98, v99
	v_cvt_pk_bf16_f32 v5, v100, v101
	ds_write_b64 v10, v[4:5] offset:8832
	v_cvt_pk_bf16_f32 v6, v166, v167
	v_cvt_pk_bf16_f32 v7, v168, v169
	ds_write_b64 v10, v[6:7] offset:416
	v_cvt_pk_bf16_f32 v8, v110, v111
	v_cvt_pk_bf16_f32 v9, v112, v113
	ds_write_b64 v10, v[8:9] offset:8864
	v_cvt_pk_bf16_f32 v2, v170, v171
	v_cvt_pk_bf16_f32 v3, v172, v173
	ds_write_b64 v10, v[2:3] offset:448
	v_cvt_pk_bf16_f32 v4, v114, v115
	v_cvt_pk_bf16_f32 v5, v116, v117
	ds_write_b64 v10, v[4:5] offset:8896
	v_cvt_pk_bf16_f32 v6, v174, v175
	v_cvt_pk_bf16_f32 v7, v176, v177
	ds_write_b64 v10, v[6:7] offset:480
	v_cvt_pk_bf16_f32 v8, v106, v107
	v_cvt_pk_bf16_f32 v9, v108, v109
	ds_write_b64 v10, v[8:9] offset:8928
	s_waitcnt lgkmcnt(0)
	ds_read_b128 v[66:69], v13 offset:0
	ds_read_b128 v[70:73], v13 offset:1056
	ds_read_b128 v[74:77], v13 offset:2112
	ds_read_b128 v[78:81], v13 offset:3168
	ds_read_b128 v[82:85], v13 offset:4224
	ds_read_b128 v[86:89], v13 offset:5280
	ds_read_b128 v[90:93], v13 offset:6336
	ds_read_b128 v[94:97], v13 offset:7392
	ds_read_b128 v[178:181], v13 offset:8448
	ds_read_b128 v[182:185], v13 offset:9504
	ds_read_b128 v[186:189], v13 offset:10560
	ds_read_b128 v[190:193], v13 offset:11616
	ds_read_b128 v[194:197], v13 offset:12672
	ds_read_b128 v[198:201], v13 offset:13728
	ds_read_b128 v[202:205], v13 offset:14784
	ds_read_b128 v[206:209], v13 offset:15840
	s_waitcnt lgkmcnt(15)
	global_store_dwordx4 v11, v[66:69], s[6:7]
	s_add_u32 s6, s6, 0x400
	s_addc_u32 s7, s7, 0
	s_waitcnt lgkmcnt(14)
	global_store_dwordx4 v11, v[70:73], s[6:7]
	s_add_u32 s6, s6, 0x400
	s_addc_u32 s7, s7, 0
	s_waitcnt lgkmcnt(13)
	global_store_dwordx4 v11, v[74:77], s[6:7]
	s_add_u32 s6, s6, 0x400
	s_addc_u32 s7, s7, 0
	s_waitcnt lgkmcnt(12)
	global_store_dwordx4 v11, v[78:81], s[6:7]
	s_add_u32 s6, s6, 0x400
	s_addc_u32 s7, s7, 0
	s_waitcnt lgkmcnt(11)
	global_store_dwordx4 v11, v[82:85], s[6:7]
	s_add_u32 s6, s6, 0x400
	s_addc_u32 s7, s7, 0
	s_waitcnt lgkmcnt(10)
	global_store_dwordx4 v11, v[86:89], s[6:7]
	s_add_u32 s6, s6, 0x400
	s_addc_u32 s7, s7, 0
	s_waitcnt lgkmcnt(9)
	global_store_dwordx4 v11, v[90:93], s[6:7]
	s_add_u32 s6, s6, 0x400
	s_addc_u32 s7, s7, 0
	s_waitcnt lgkmcnt(8)
	global_store_dwordx4 v11, v[94:97], s[6:7]
	s_add_u32 s6, s6, 0x400
	s_addc_u32 s7, s7, 0
	s_waitcnt lgkmcnt(7)
	global_store_dwordx4 v11, v[178:181], s[6:7]
	s_add_u32 s6, s6, 0x400
	s_addc_u32 s7, s7, 0
	s_waitcnt lgkmcnt(6)
	global_store_dwordx4 v11, v[182:185], s[6:7]
	s_add_u32 s6, s6, 0x400
	s_addc_u32 s7, s7, 0
	s_waitcnt lgkmcnt(5)
	global_store_dwordx4 v11, v[186:189], s[6:7]
	s_add_u32 s6, s6, 0x400
	s_addc_u32 s7, s7, 0
	s_waitcnt lgkmcnt(4)
	global_store_dwordx4 v11, v[190:193], s[6:7]
	s_add_u32 s6, s6, 0x400
	s_addc_u32 s7, s7, 0
	s_waitcnt lgkmcnt(3)
	global_store_dwordx4 v11, v[194:197], s[6:7]
	s_add_u32 s6, s6, 0x400
	s_addc_u32 s7, s7, 0
	s_waitcnt lgkmcnt(2)
	global_store_dwordx4 v11, v[198:201], s[6:7]
	s_add_u32 s6, s6, 0x400
	s_addc_u32 s7, s7, 0
	s_waitcnt lgkmcnt(1)
	global_store_dwordx4 v11, v[202:205], s[6:7]
	s_add_u32 s6, s6, 0x400
	s_addc_u32 s7, s7, 0
	s_waitcnt lgkmcnt(0)
	global_store_dwordx4 v11, v[206:209], s[6:7]
	s_add_i32 s12, s12, s93
	s_cmpk_lt_i32 s12, 0x200
	s_waitcnt lgkmcnt(0)
	s_barrier
	s_cbranch_scc0 .Lmy_cmp_exit

; #define NEG_INF (-__builtin_inff())
; DEV unsigned cvtpk(float lo, float hi) { typedef float f2 __attribute__((ext_vector_type(2))); typedef __bf16 b2 __attribute__((ext_vector_type(2))); f2 v = {lo, hi}; b2 b = __builtin_convertvector(v, b2); return __builtin_bit_cast(unsigned, b); }
; DEV void ref_step(f32x4 (&s)[4], float& m, f32x4 (&O)[4], f32x4& L, ab8 (&pf)[2], bool colact) {
;     float mx = fmaxf(fmaxf(s[0][0], s[0][1]), fmaxf(s[0][2], s[0][3]));
; #pragma unroll
;     for (int kt = 1; kt < 4; ++kt) mx = fmaxf(mx, fmaxf(fmaxf(s[kt][0], s[kt][1]), fmaxf(s[kt][2], s[kt][3])));
;     const bool slow = (colact && m == NEG_INF) || mx > 64.f;
;     if (__any(slow)) {
;         mx = fmaxf(mx, __shfl_xor(mx, 16)); mx = fmaxf(mx, __shfl_xor(mx, 32));
;         const bool un = (m == NEG_INF);
;         const float d = (mx == NEG_INF) ? 0.f : (un ? mx : fmaxf(mx, 0.f));
;         const float sc = un ? 1.f : __builtin_amdgcn_exp2f(-d);
; #pragma unroll
;         for (int kt = 0; kt < 4; ++kt) s[kt] = s[kt] - d;
; #pragma unroll
;         for (int dt = 0; dt < 4; ++dt) O[dt] = O[dt] * sc;
;         L = L * sc;
;         m = un ? ((mx == NEG_INF) ? NEG_INF : mx) : m + d;
;     }
; #pragma unroll
;     for (int kt = 0; kt < 4; ++kt)
; #pragma unroll
;         for (int i = 0; i < 4; ++i) s[kt][i] = __builtin_amdgcn_exp2f(s[kt][i]);
; #pragma unroll
;     for (int j = 0; j < 2; ++j) { v4u w; w.x = cvtpk(s[2 * j][0], s[2 * j][1]); w.y = cvtpk(s[2 * j][2], s[2 * j][3]); w.z = cvtpk(s[2 * j + 1][0], s[2 * j + 1][1]); w.w = cvtpk(s[2 * j + 1][2], s[2 * j + 1][3]); pf[j] = __builtin_bit_cast(ab8, w); }
; }
; DEV void attn_unit_mfma(Frame& F, int qg, int kv) {
;     ...
;         const int j = lst[1 + i]; const unsigned byte = (msk[2 * j + (w >> 2)] >> (8 * (w & 3))) & 0xffu;
;         const bool a0 = (byte & 0xfu) != 0u, a1 = (byte & 0xf0u) != 0u;
;         if (a0 || a1) {
;             const bool near = j >= cur - 2; const float bi = near ? 0.f : C.b31;
;             const bool c0 = ((byte >> (C.n >> 2)) & 1u) != 0u, c1 = ((byte >> (4 + (C.n >> 2))) & 1u) != 0u;
;     ...
;             if (a0 && a1) SEL_BODY(true, true); else if (a0) SEL_BODY(true, false); else SEL_BODY(false, true);
.Lmy_sel_pd:
.LBB0_1171:
	s_mul_i32 s8, s8, 0xc000
	s_add_i32 s9, s28, -2
	s_add_i32 s27, s8, 0
	s_cmp_ge_i32 s9, s23
	s_cbranch_scc1 .LBB0_1196
	s_waitcnt lgkmcnt(0)
	s_and_b32 s29, s98, 0xffff
	s_lshr_b32 s8, s98, 16
	s_and_b32 s9, s8, 0xff
	s_cmp_eq_u32 s9, 0
	s_cbranch_scc1 .LBB0_1196
	s_cmp_ge_i32 s29, s22
	s_cbranch_scc1 .Lmy_orig_0
	s_and_b32 s9, s8, 15
	s_and_b32 s10, s8, 0xf0
	s_cmp_lg_u32 s9, 0
	s_cselect_b32 s11, 1, 0
	s_cmp_lg_u32 s10, 0
	s_cselect_b32 s12, 1, 0
	s_add_i32 s13, s11, s12
	s_cmp_eq_u32 s13, 2
	s_cbranch_scc1 .Lmy_fb_0
	s_cmp_eq_u32 s11, 1
	s_cbranch_scc0 .Lmy_f1_0
	v_add3_u32 v228, s27, v199, v198
	v_add3_u32 v229, s27, v197, v198
	ds_read_b128 v[66:69], v228 offset:0
	ds_read_b128 v[70:73], v229 offset:0
	ds_read_b128 v[74:77], v228 offset:2048
	ds_read_b128 v[78:81], v229 offset:2048
	ds_read_b128 v[82:85], v228 offset:4096
	ds_read_b128 v[86:89], v229 offset:4096
	ds_read_b128 v[90:93], v228 offset:6144
	ds_read_b128 v[94:97], v229 offset:6144
	v_and_b32_e32 v239, s8, v206
	v_cmp_ne_u32_e64 s[10:11], 0, v239
	v_cmp_eq_f32_e64 s[12:13], s3, v213
	v_add_u32_e32 v234, s27, v200
	v_add3_u32 v235, v234, v201, v209
	v_add3_u32 v236, v234, v202, v209
	v_cndmask_b32_e64 v230, v213, 0, s[12:13]
	v_sub_f32_e32 v230, v175, v230
	v_add3_u32 v237, v234, v203, v209
	v_add3_u32 v238, v234, v204, v209
	v_cndmask_b32_e64 v230, v173, v230, s[10:11]
	v_mov_b32_e32 v231, v230
	v_mov_b32_e32 v232, v230
	v_mov_b32_e32 v233, v230
	s_and_b64 s[12:13], s[10:11], s[12:13]
	s_waitcnt lgkmcnt(0)
	v_mfma_f32_16x16x32_bf16 v[66:69], v[66:69], v[2:5], v[230:233]
	v_mfma_f32_16x16x32_bf16 v[74:77], v[74:77], v[2:5], v[230:233]
	v_mfma_f32_16x16x32_bf16 v[82:85], v[82:85], v[2:5], v[230:233]
	v_mfma_f32_16x16x32_bf16 v[90:93], v[90:93], v[2:5], v[230:233]
	v_mfma_f32_16x16x32_bf16 v[66:69], v[70:73], v[6:9], v[66:69]
	v_mfma_f32_16x16x32_bf16 v[74:77], v[78:81], v[6:9], v[74:77]
	v_mfma_f32_16x16x32_bf16 v[82:85], v[86:89], v[6:9], v[82:85]
	v_mfma_f32_16x16x32_bf16 v[90:93], v[94:97], v[6:9], v[90:93]
	ds_read_b64_tr_b16 v[98:99], v235 offset:8192
	ds_read_b64_tr_b16 v[100:101], v235 offset:10240
	ds_read_b64_tr_b16 v[102:103], v235 offset:12288
	ds_read_b64_tr_b16 v[104:105], v235 offset:14336
	ds_read_b64_tr_b16 v[106:107], v236 offset:8192
	ds_read_b64_tr_b16 v[108:109], v236 offset:10240
	ds_read_b64_tr_b16 v[110:111], v236 offset:12288
	ds_read_b64_tr_b16 v[112:113], v236 offset:14336
	ds_read_b64_tr_b16 v[114:115], v237 offset:8192
	ds_read_b64_tr_b16 v[116:117], v237 offset:10240
	ds_read_b64_tr_b16 v[118:119], v237 offset:12288
	ds_read_b64_tr_b16 v[120:121], v237 offset:14336
	ds_read_b64_tr_b16 v[122:123], v238 offset:8192
	ds_read_b64_tr_b16 v[124:125], v238 offset:10240
	ds_read_b64_tr_b16 v[126:127], v238 offset:12288
	ds_read_b64_tr_b16 v[128:129], v238 offset:14336
	v_max3_f32 v239, v66, v67, v68
	v_max3_f32 v240, v69, v74, v75
	v_max3_f32 v241, v76, v77, v82
	v_max3_f32 v242, v83, v84, v85
	v_max3_f32 v239, v239, v240, v90
	v_max3_f32 v241, v241, v242, v91
	v_max3_f32 v239, v239, v92, v93
	v_max_f32_e32 v239, v239, v241
	v_cmp_lt_f32_e32 vcc, s96, v239
	s_or_b64 s[12:13], s[12:13], vcc
	s_cmp_lg_u64 s[12:13], 0
	s_cbranch_scc1 .Lmy_slow_0_0
	v_exp_f32_e32 v66, v66
	v_exp_f32_e32 v67, v67
	v_exp_f32_e32 v68, v68
	v_exp_f32_e32 v69, v69
	v_exp_f32_e32 v74, v74
	v_exp_f32_e32 v75, v75
	v_exp_f32_e32 v76, v76
	v_exp_f32_e32 v77, v77
	v_exp_f32_e32 v82, v82
	v_exp_f32_e32 v83, v83
	v_exp_f32_e32 v84, v84
	v_exp_f32_e32 v85, v85
	v_exp_f32_e32 v90, v90
	v_exp_f32_e32 v91, v91
	v_exp_f32_e32 v92, v92
	v_exp_f32_e32 v93, v93
	v_cvt_pk_bf16_f32 v130, v66, v67
	v_cvt_pk_bf16_f32 v131, v68, v69
	v_cvt_pk_bf16_f32 v132, v74, v75
	v_cvt_pk_bf16_f32 v133, v76, v77
	v_cvt_pk_bf16_f32 v134, v82, v83
	v_cvt_pk_bf16_f32 v135, v84, v85
	v_cvt_pk_bf16_f32 v136, v90, v91
	v_cvt_pk_bf16_f32 v137, v92, v93
	s_nop 1
	s_waitcnt lgkmcnt(12)
	v_mfma_f32_16x16x32_bf16 v[62:65], v[98:101], v[130:133], v[62:65]
	v_mfma_f32_16x16x32_bf16 v[58:61], v[22:25], v[130:133], v[58:61]
	v_mfma_f32_16x16x32_bf16 v[62:65], v[102:105], v[134:137], v[62:65]
	s_waitcnt lgkmcnt(8)
	v_mfma_f32_16x16x32_bf16 v[54:57], v[106:109], v[130:133], v[54:57]
	v_mfma_f32_16x16x32_bf16 v[54:57], v[110:113], v[134:137], v[54:57]
	s_waitcnt lgkmcnt(4)
	v_mfma_f32_16x16x32_bf16 v[50:53], v[114:117], v[130:133], v[50:53]
	v_mfma_f32_16x16x32_bf16 v[58:61], v[22:25], v[134:137], v[58:61]
	v_mfma_f32_16x16x32_bf16 v[50:53], v[118:121], v[134:137], v[50:53]
	s_waitcnt lgkmcnt(0)
	v_mfma_f32_16x16x32_bf16 v[46:49], v[122:125], v[130:133], v[46:49]
	v_mfma_f32_16x16x32_bf16 v[46:49], v[126:129], v[134:137], v[46:49]
	s_nop 7
	s_branch .LBB0_1196

; #define NEG_INF (-__builtin_inff())
; DEV unsigned cvtpk(float lo, float hi) { typedef float f2 __attribute__((ext_vector_type(2))); typedef __bf16 b2 __attribute__((ext_vector_type(2))); f2 v = {lo, hi}; b2 b = __builtin_convertvector(v, b2); return __builtin_bit_cast(unsigned, b); }
; DEV void ref_step(f32x4 (&s)[4], float& m, f32x4 (&O)[4], f32x4& L, ab8 (&pf)[2], bool colact) {
;     float mx = fmaxf(fmaxf(s[0][0], s[0][1]), fmaxf(s[0][2], s[0][3]));
; #pragma unroll
;     for (int kt = 1; kt < 4; ++kt) mx = fmaxf(mx, fmaxf(fmaxf(s[kt][0], s[kt][1]), fmaxf(s[kt][2], s[kt][3])));
;     const bool slow = (colact && m == NEG_INF) || mx > 64.f;
;     if (__any(slow)) {
;         mx = fmaxf(mx, __shfl_xor(mx, 16)); mx = fmaxf(mx, __shfl_xor(mx, 32));
;         const bool un = (m == NEG_INF);
;         const float d = (mx == NEG_INF) ? 0.f : (un ? mx : fmaxf(mx, 0.f));
;         const float sc = un ? 1.f : __builtin_amdgcn_exp2f(-d);
; #pragma unroll
;         for (int kt = 0; kt < 4; ++kt) s[kt] = s[kt] - d;
; #pragma unroll
;         for (int dt = 0; dt < 4; ++dt) O[dt] = O[dt] * sc;
;         L = L * sc;
;         m = un ? ((mx == NEG_INF) ? NEG_INF : mx) : m + d;
;     }
; #pragma unroll
;     for (int kt = 0; kt < 4; ++kt)
; #pragma unroll
;         for (int i = 0; i < 4; ++i) s[kt][i] = __builtin_amdgcn_exp2f(s[kt][i]);
; #pragma unroll
;     for (int j = 0; j < 2; ++j) { v4u w; w.x = cvtpk(s[2 * j][0], s[2 * j][1]); w.y = cvtpk(s[2 * j][2], s[2 * j][3]); w.z = cvtpk(s[2 * j + 1][0], s[2 * j + 1][1]); w.w = cvtpk(s[2 * j + 1][2], s[2 * j + 1][3]); pf[j] = __builtin_bit_cast(ab8, w); }
; }
; DEV void attn_unit_mfma(Frame& F, int qg, int kv) {
;     ...
;         const int j = lst[1 + i]; const unsigned byte = (msk[2 * j + (w >> 2)] >> (8 * (w & 3))) & 0xffu;
;         const bool a0 = (byte & 0xfu) != 0u, a1 = (byte & 0xf0u) != 0u;
;         if (a0 || a1) {
;             const bool near = j >= cur - 2; const float bi = near ? 0.f : C.b31;
;             const bool c0 = ((byte >> (C.n >> 2)) & 1u) != 0u, c1 = ((byte >> (4 + (C.n >> 2))) & 1u) != 0u;
;     ...
;             if (a0 && a1) SEL_BODY(true, true); else if (a0) SEL_BODY(true, false); else SEL_BODY(false, true);
.Lmy_f1_0:
	v_add3_u32 v228, s27, v199, v198
	v_add3_u32 v229, s27, v197, v198
	ds_read_b128 v[66:69], v228 offset:0
	ds_read_b128 v[70:73], v229 offset:0
	ds_read_b128 v[74:77], v228 offset:2048
	ds_read_b128 v[78:81], v229 offset:2048
	ds_read_b128 v[82:85], v228 offset:4096
	ds_read_b128 v[86:89], v229 offset:4096
	ds_read_b128 v[90:93], v228 offset:6144
	ds_read_b128 v[94:97], v229 offset:6144
	v_and_b32_e32 v239, s8, v207
	v_cmp_ne_u32_e64 s[10:11], 0, v239
	v_cmp_eq_f32_e64 s[12:13], s3, v212
	v_add_u32_e32 v234, s27, v200
	v_add3_u32 v235, v234, v201, v209
	v_add3_u32 v236, v234, v202, v209
	v_cndmask_b32_e64 v230, v212, 0, s[12:13]
	v_sub_f32_e32 v230, v175, v230
	v_add3_u32 v237, v234, v203, v209
	v_add3_u32 v238, v234, v204, v209
	v_cndmask_b32_e64 v230, v173, v230, s[10:11]
	v_mov_b32_e32 v231, v230
	v_mov_b32_e32 v232, v230
	v_mov_b32_e32 v233, v230
	s_and_b64 s[12:13], s[10:11], s[12:13]
	s_waitcnt lgkmcnt(0)
	v_mfma_f32_16x16x32_bf16 v[66:69], v[66:69], v[10:13], v[230:233]
	v_mfma_f32_16x16x32_bf16 v[74:77], v[74:77], v[10:13], v[230:233]
	v_mfma_f32_16x16x32_bf16 v[82:85], v[82:85], v[10:13], v[230:233]
	v_mfma_f32_16x16x32_bf16 v[90:93], v[90:93], v[10:13], v[230:233]
	v_mfma_f32_16x16x32_bf16 v[66:69], v[70:73], v[14:17], v[66:69]
	v_mfma_f32_16x16x32_bf16 v[74:77], v[78:81], v[14:17], v[74:77]
	v_mfma_f32_16x16x32_bf16 v[82:85], v[86:89], v[14:17], v[82:85]
	v_mfma_f32_16x16x32_bf16 v[90:93], v[94:97], v[14:17], v[90:93]
	ds_read_b64_tr_b16 v[98:99], v235 offset:8192
	ds_read_b64_tr_b16 v[100:101], v235 offset:10240
	ds_read_b64_tr_b16 v[102:103], v235 offset:12288
	ds_read_b64_tr_b16 v[104:105], v235 offset:14336
	ds_read_b64_tr_b16 v[106:107], v236 offset:8192
	ds_read_b64_tr_b16 v[108:109], v236 offset:10240
	ds_read_b64_tr_b16 v[110:111], v236 offset:12288
	ds_read_b64_tr_b16 v[112:113], v236 offset:14336
	ds_read_b64_tr_b16 v[114:115], v237 offset:8192
	ds_read_b64_tr_b16 v[116:117], v237 offset:10240
	ds_read_b64_tr_b16 v[118:119], v237 offset:12288
	ds_read_b64_tr_b16 v[120:121], v237 offset:14336
	ds_read_b64_tr_b16 v[122:123], v238 offset:8192
	ds_read_b64_tr_b16 v[124:125], v238 offset:10240
	ds_read_b64_tr_b16 v[126:127], v238 offset:12288
	ds_read_b64_tr_b16 v[128:129], v238 offset:14336
	v_max3_f32 v239, v66, v67, v68
	v_max3_f32 v240, v69, v74, v75
	v_max3_f32 v241, v76, v77, v82
	v_max3_f32 v242, v83, v84, v85
	v_max3_f32 v239, v239, v240, v90
	v_max3_f32 v241, v241, v242, v91
	v_max3_f32 v239, v239, v92, v93
	v_max_f32_e32 v239, v239, v241
	v_cmp_lt_f32_e32 vcc, s96, v239
	s_or_b64 s[12:13], s[12:13], vcc
	s_cmp_lg_u64 s[12:13], 0
	s_cbranch_scc1 .Lmy_slow_1_0
	v_exp_f32_e32 v66, v66
	v_exp_f32_e32 v67, v67
	v_exp_f32_e32 v68, v68
	v_exp_f32_e32 v69, v69
	v_exp_f32_e32 v74, v74
	v_exp_f32_e32 v75, v75
	v_exp_f32_e32 v76, v76
	v_exp_f32_e32 v77, v77
	v_exp_f32_e32 v82, v82
	v_exp_f32_e32 v83, v83
	v_exp_f32_e32 v84, v84
	v_exp_f32_e32 v85, v85
	v_exp_f32_e32 v90, v90
	v_exp_f32_e32 v91, v91
	v_exp_f32_e32 v92, v92
	v_exp_f32_e32 v93, v93
	v_cvt_pk_bf16_f32 v130, v66, v67
	v_cvt_pk_bf16_f32 v131, v68, v69
	v_cvt_pk_bf16_f32 v132, v74, v75
	v_cvt_pk_bf16_f32 v133, v76, v77
	v_cvt_pk_bf16_f32 v134, v82, v83
	v_cvt_pk_bf16_f32 v135, v84, v85
	v_cvt_pk_bf16_f32 v136, v90, v91
	v_cvt_pk_bf16_f32 v137, v92, v93
	s_nop 1
	s_waitcnt lgkmcnt(12)
	v_mfma_f32_16x16x32_bf16 v[38:41], v[98:101], v[130:133], v[38:41]
	v_mfma_f32_16x16x32_bf16 v[42:45], v[22:25], v[130:133], v[42:45]
	v_mfma_f32_16x16x32_bf16 v[38:41], v[102:105], v[134:137], v[38:41]
	s_waitcnt lgkmcnt(8)
	v_mfma_f32_16x16x32_bf16 v[34:37], v[106:109], v[130:133], v[34:37]
	v_mfma_f32_16x16x32_bf16 v[34:37], v[110:113], v[134:137], v[34:37]
	s_waitcnt lgkmcnt(4)
	v_mfma_f32_16x16x32_bf16 v[30:33], v[114:117], v[130:133], v[30:33]
	v_mfma_f32_16x16x32_bf16 v[42:45], v[22:25], v[134:137], v[42:45]
	v_mfma_f32_16x16x32_bf16 v[30:33], v[118:121], v[134:137], v[30:33]
	s_waitcnt lgkmcnt(0)
	v_mfma_f32_16x16x32_bf16 v[26:29], v[122:125], v[130:133], v[26:29]
	v_mfma_f32_16x16x32_bf16 v[26:29], v[126:129], v[134:137], v[26:29]
	s_nop 7
	s_branch .LBB0_1196

; #define NEG_INF (-__builtin_inff())
; DEV void qk64(const LAS unsigned char* Kb, const AttnCtx& C, const ab8 (&qf)[2][2], f32x4 (&s)[2][4], float init0, float init1, bool a0, bool a1) {
;     ab8 k0[4], k1[4];
; #pragma unroll
;     for (int kt = 0; kt < 4; ++kt) { k0[kt] = *(const LAS ab8*)(Kb + swz(16 * kt + C.n, C.q4)); k1[kt] = *(const LAS ab8*)(Kb + swz(16 * kt + C.n, 4 + C.q4)); }
;     __builtin_amdgcn_sched_barrier(0);
; #pragma unroll
;     for (int kt = 0; kt < 4; ++kt) {
;         if (a0) { f32x4 c = {init0, init0, init0, init0}; c = __builtin_amdgcn_mfma_f32_16x16x32_bf16(k0[kt], qf[0][0], c, 0, 0, 0); s[0][kt] = __builtin_amdgcn_mfma_f32_16x16x32_bf16(k1[kt], qf[0][1], c, 0, 0, 0); }
;         if (a1) { f32x4 c = {init1, init1, init1, init1}; c = __builtin_amdgcn_mfma_f32_16x16x32_bf16(k0[kt], qf[1][0], c, 0, 0, 0); s[1][kt] = __builtin_amdgcn_mfma_f32_16x16x32_bf16(k1[kt], qf[1][1], c, 0, 0, 0); }
;     }
; }
; template <bool LUTB, bool WINLO>
; DEV void mask_bias(f32x4 (&s)[4], const AttnCtx& C, int t, int p0, int pstep, bool colok) {
; #pragma unroll
;     for (int kt = 0; kt < 4; ++kt)
; #pragma unroll
;         for (int i = 0; i < 4; ++i) { const int rel = t - (p0 + pstep * (16 * kt + 4 * C.q4 + i));
;             bool ok = colok && rel >= 0; if (WINLO) ok = ok && rel < 512;
;             float v = s[kt][i]; if (LUTB) v += C.lut[C.h * 129 + (rel < 0 ? 0 : (rel < 128 ? rel : 128))];
;             s[kt][i] = ok ? v : NEG_INF; }
; }
; DEV float colmax16(const f32x4 (&s)[4]) {
;     float mx = fmaxf(fmaxf(s[0][0], s[0][1]), fmaxf(s[0][2], s[0][3]));
; #pragma unroll
;     for (int kt = 1; kt < 4; ++kt) mx = fmaxf(mx, fmaxf(fmaxf(s[kt][0], s[kt][1]), fmaxf(s[kt][2], s[kt][3])));
;     mx = fmaxf(mx, __shfl_xor(mx, 16)); mx = fmaxf(mx, __shfl_xor(mx, 32));
;     return mx;
; }
; DEV void attn_unit_mfma(Frame& F, int qg, int kv) {
;     ...
;         const int j = lst[1 + i]; const unsigned byte = (msk[2 * j + (w >> 2)] >> (8 * (w & 3))) & 0xffu;
;         const bool a0 = (byte & 0xfu) != 0u, a1 = (byte & 0xf0u) != 0u;
;         if (a0 || a1) {
;             const bool near = j >= cur - 2; const float bi = near ? 0.f : C.b31;
;             const bool c0 = ((byte >> (C.n >> 2)) & 1u) != 0u, c1 = ((byte >> (4 + (C.n >> 2))) & 1u) != 0u;
;     ...
;             if (a0 && a1) SEL_BODY(true, true); else if (a0) SEL_BODY(true, false); else SEL_BODY(false, true);
.Lmy_fb_0:
	v_add3_u32 v236, s27, v199, v198
	v_add3_u32 v237, s27, v197, v198
	ds_read_b128 v[66:69], v236 offset:0
	ds_read_b128 v[70:73], v237 offset:0
	ds_read_b128 v[74:77], v236 offset:2048
	ds_read_b128 v[78:81], v237 offset:2048
	ds_read_b128 v[82:85], v236 offset:4096
	ds_read_b128 v[86:89], v237 offset:4096
	ds_read_b128 v[90:93], v236 offset:6144
	ds_read_b128 v[94:97], v237 offset:6144
	v_and_b32_e32 v243, s8, v206
	v_and_b32_e32 v244, s8, v207
	v_cmp_ne_u32_e64 s[10:11], 0, v243
	v_cmp_ne_u32_e64 s[14:15], 0, v244
	v_cmp_eq_f32_e64 s[12:13], s3, v213
	v_cmp_eq_f32_e64 s[16:17], s3, v212
	v_add_u32_e32 v238, s27, v200
	v_add3_u32 v239, v238, v201, v209
	v_add3_u32 v240, v238, v202, v209
	v_cndmask_b32_e64 v228, v213, 0, s[12:13]
	v_cndmask_b32_e64 v232, v212, 0, s[16:17]
	v_sub_f32_e32 v228, v175, v228
	v_sub_f32_e32 v232, v175, v232
	v_add3_u32 v241, v238, v203, v209
	v_add3_u32 v242, v238, v204, v209
	v_cndmask_b32_e64 v228, v173, v228, s[10:11]
	v_cndmask_b32_e64 v232, v173, v232, s[14:15]
	v_mov_b32_e32 v229, v228
	v_mov_b32_e32 v230, v228
	v_mov_b32_e32 v231, v228
	v_mov_b32_e32 v233, v232
	v_mov_b32_e32 v234, v232
	v_mov_b32_e32 v235, v232
	s_and_b64 s[12:13], s[10:11], s[12:13]
	s_and_b64 s[16:17], s[14:15], s[16:17]
	s_or_b64 s[12:13], s[12:13], s[16:17]
	s_waitcnt lgkmcnt(0)
	v_mfma_f32_16x16x32_bf16 v[98:101], v[66:69], v[10:13], v[232:235]
	v_mfma_f32_16x16x32_bf16 v[102:105], v[74:77], v[10:13], v[232:235]
	v_mfma_f32_16x16x32_bf16 v[106:109], v[82:85], v[10:13], v[232:235]
	v_mfma_f32_16x16x32_bf16 v[110:113], v[90:93], v[10:13], v[232:235]
	v_mfma_f32_16x16x32_bf16 v[66:69], v[66:69], v[2:5], v[228:231]
	v_mfma_f32_16x16x32_bf16 v[74:77], v[74:77], v[2:5], v[228:231]
	v_mfma_f32_16x16x32_bf16 v[82:85], v[82:85], v[2:5], v[228:231]
	v_mfma_f32_16x16x32_bf16 v[90:93], v[90:93], v[2:5], v[228:231]
	v_mfma_f32_16x16x32_bf16 v[66:69], v[70:73], v[6:9], v[66:69]
	v_mfma_f32_16x16x32_bf16 v[74:77], v[78:81], v[6:9], v[74:77]
	v_mfma_f32_16x16x32_bf16 v[82:85], v[86:89], v[6:9], v[82:85]
	v_mfma_f32_16x16x32_bf16 v[90:93], v[94:97], v[6:9], v[90:93]
	v_mfma_f32_16x16x32_bf16 v[70:73], v[70:73], v[14:17], v[98:101]
	v_mfma_f32_16x16x32_bf16 v[78:81], v[78:81], v[14:17], v[102:105]
	v_mfma_f32_16x16x32_bf16 v[86:89], v[86:89], v[14:17], v[106:109]
	v_mfma_f32_16x16x32_bf16 v[94:97], v[94:97], v[14:17], v[110:113]
	ds_read_b64_tr_b16 v[114:115], v241 offset:8192
	ds_read_b64_tr_b16 v[116:117], v241 offset:10240
	ds_read_b64_tr_b16 v[118:119], v241 offset:12288
	ds_read_b64_tr_b16 v[120:121], v241 offset:14336
	ds_read_b64_tr_b16 v[122:123], v242 offset:8192
	ds_read_b64_tr_b16 v[124:125], v242 offset:10240
	ds_read_b64_tr_b16 v[126:127], v242 offset:12288
	ds_read_b64_tr_b16 v[128:129], v242 offset:14336
	ds_read_b64_tr_b16 v[98:99], v239 offset:8192
	ds_read_b64_tr_b16 v[100:101], v239 offset:10240
	ds_read_b64_tr_b16 v[102:103], v239 offset:12288
	ds_read_b64_tr_b16 v[104:105], v239 offset:14336
	ds_read_b64_tr_b16 v[106:107], v240 offset:8192
	ds_read_b64_tr_b16 v[108:109], v240 offset:10240
	ds_read_b64_tr_b16 v[110:111], v240 offset:12288
	ds_read_b64_tr_b16 v[112:113], v240 offset:14336
	v_max3_f32 v243, v66, v67, v68
	v_max3_f32 v244, v69, v74, v75
	v_max3_f32 v245, v76, v77, v82
	v_max3_f32 v246, v83, v84, v85
	v_max3_f32 v243, v243, v244, v90
	v_max3_f32 v245, v245, v246, v91
	v_max3_f32 v243, v243, v92, v93
	v_max_f32_e32 v243, v243, v245
	v_cmp_lt_f32_e32 vcc, s96, v243
	s_or_b64 s[12:13], s[12:13], vcc
	v_max3_f32 v243, v70, v71, v72
	v_max3_f32 v244, v73, v78, v79
	v_max3_f32 v245, v80, v81, v86
	v_max3_f32 v246, v87, v88, v89
	v_max3_f32 v243, v243, v244, v94
	v_max3_f32 v245, v245, v246, v95
	v_max3_f32 v243, v243, v96, v97
	v_max_f32_e32 v243, v243, v245
	v_cmp_lt_f32_e32 vcc, s96, v243
	s_or_b64 s[12:13], s[12:13], vcc
	s_cmp_lg_u64 s[12:13], 0
	s_cbranch_scc1 .Lmy_slow_b_0
	v_exp_f32_e32 v66, v66
	v_exp_f32_e32 v67, v67
	v_exp_f32_e32 v68, v68
	v_exp_f32_e32 v69, v69
	v_exp_f32_e32 v74, v74
	v_exp_f32_e32 v75, v75
	v_exp_f32_e32 v76, v76
	v_exp_f32_e32 v77, v77
	v_exp_f32_e32 v82, v82
	v_exp_f32_e32 v83, v83
	v_exp_f32_e32 v84, v84
	v_exp_f32_e32 v85, v85
	v_exp_f32_e32 v90, v90
	v_exp_f32_e32 v91, v91
	v_exp_f32_e32 v92, v92
	v_exp_f32_e32 v93, v93
	v_exp_f32_e32 v70, v70
	v_exp_f32_e32 v71, v71
	v_exp_f32_e32 v72, v72
	v_exp_f32_e32 v73, v73
	v_exp_f32_e32 v78, v78
	v_exp_f32_e32 v79, v79
	v_exp_f32_e32 v80, v80
	v_exp_f32_e32 v81, v81
	v_exp_f32_e32 v86, v86
	v_exp_f32_e32 v87, v87
	v_exp_f32_e32 v88, v88
	v_exp_f32_e32 v89, v89
	v_exp_f32_e32 v94, v94
	v_exp_f32_e32 v95, v95
	v_exp_f32_e32 v96, v96
	v_exp_f32_e32 v97, v97
	v_cvt_pk_bf16_f32 v130, v66, v67
	v_cvt_pk_bf16_f32 v131, v68, v69
	v_cvt_pk_bf16_f32 v132, v74, v75
	v_cvt_pk_bf16_f32 v133, v76, v77
	v_cvt_pk_bf16_f32 v134, v82, v83
	v_cvt_pk_bf16_f32 v135, v84, v85
	v_cvt_pk_bf16_f32 v136, v90, v91
	v_cvt_pk_bf16_f32 v137, v92, v93
	v_cvt_pk_bf16_f32 v228, v70, v71
	v_cvt_pk_bf16_f32 v229, v72, v73
	v_cvt_pk_bf16_f32 v230, v78, v79
	v_cvt_pk_bf16_f32 v231, v80, v81
	v_cvt_pk_bf16_f32 v232, v86, v87
	v_cvt_pk_bf16_f32 v233, v88, v89
	v_cvt_pk_bf16_f32 v234, v94, v95
	v_cvt_pk_bf16_f32 v235, v96, v97
	s_nop 1
	s_waitcnt lgkmcnt(12)
	v_mfma_f32_16x16x32_bf16 v[50:53], v[114:117], v[130:133], v[50:53]
	v_mfma_f32_16x16x32_bf16 v[30:33], v[114:117], v[228:231], v[30:33]
	v_mfma_f32_16x16x32_bf16 v[58:61], v[22:25], v[130:133], v[58:61]
	v_mfma_f32_16x16x32_bf16 v[42:45], v[22:25], v[228:231], v[42:45]
	v_mfma_f32_16x16x32_bf16 v[50:53], v[118:121], v[134:137], v[50:53]
	v_mfma_f32_16x16x32_bf16 v[30:33], v[118:121], v[232:235], v[30:33]
	s_waitcnt lgkmcnt(8)
	v_mfma_f32_16x16x32_bf16 v[46:49], v[122:125], v[130:133], v[46:49]
	v_mfma_f32_16x16x32_bf16 v[26:29], v[122:125], v[228:231], v[26:29]
	v_mfma_f32_16x16x32_bf16 v[46:49], v[126:129], v[134:137], v[46:49]
	v_mfma_f32_16x16x32_bf16 v[26:29], v[126:129], v[232:235], v[26:29]
	s_waitcnt lgkmcnt(4)
	v_mfma_f32_16x16x32_bf16 v[62:65], v[98:101], v[130:133], v[62:65]
	v_mfma_f32_16x16x32_bf16 v[38:41], v[98:101], v[228:231], v[38:41]
	v_mfma_f32_16x16x32_bf16 v[58:61], v[22:25], v[134:137], v[58:61]
	v_mfma_f32_16x16x32_bf16 v[42:45], v[22:25], v[232:235], v[42:45]
	v_mfma_f32_16x16x32_bf16 v[62:65], v[102:105], v[134:137], v[62:65]
	v_mfma_f32_16x16x32_bf16 v[38:41], v[102:105], v[232:235], v[38:41]
	s_waitcnt lgkmcnt(0)
	v_mfma_f32_16x16x32_bf16 v[54:57], v[106:109], v[130:133], v[54:57]
	v_mfma_f32_16x16x32_bf16 v[34:37], v[106:109], v[228:231], v[34:37]
	v_mfma_f32_16x16x32_bf16 v[54:57], v[110:113], v[134:137], v[54:57]
	v_mfma_f32_16x16x32_bf16 v[34:37], v[110:113], v[232:235], v[34:37]
	s_nop 7
	s_branch .LBB0_1196

; #define LAS __attribute__((address_space(3)))
; #define SS_ISSUE(t, slot) do { LAS unsigned char* d_ = lbase + (slot) * 2 * TILEB; const size_t gb_ = (size_t)rowfn(t) * 256 + goff; \
;         __builtin_amdgcn_global_load_lds((const unsigned*)((const char*)Kg + gb_), (LAS unsigned*)d_, 16, 0, 0); \
;         __builtin_amdgcn_global_load_lds((const unsigned*)((const char*)Vg + gb_), (LAS unsigned*)(d_ + TILEB), 16, 0, 0); } while (0)
; template <int NB, class RowFn, class Compute>
; DEV void stream_stages_dma(Frame& F, int n, const bf16* Kg, const bf16* Vg, RowFn rowfn, Compute compute) {
;     ...
;         for (int b = 0; b < NB; ++b) if (i0 + NB + b < n) SS_ISSUE(i0 + NB + b, (st ^ 1) * NB + b);
;         const LAS unsigned char* cur = F.lds + st * NB * 2 * TILEB;
; #pragma unroll
;         for (int b = 0; b < NB; ++b) if (i0 + b < n) compute(i0 + b, cur + b * 2 * TILEB, cur + b * 2 * TILEB + TILEB);
; DEV void attn_unit_mfma(Frame& F, int qg, int kv) {
;     ...
;         const int j = lst[1 + i]; const unsigned byte = (msk[2 * j + (w >> 2)] >> (8 * (w & 3))) & 0xffu;
;         const bool a0 = (byte & 0xfu) != 0u, a1 = (byte & 0xf0u) != 0u;
;         if (a0 || a1) {
;             const bool near = j >= cur - 2; const float bi = near ? 0.f : C.b31;
;             const bool c0 = ((byte >> (C.n >> 2)) & 1u) != 0u, c1 = ((byte >> (4 + (C.n >> 2))) & 1u) != 0u;
;     ...
;             if (a0 && a1) SEL_BODY(true, true); else if (a0) SEL_BODY(true, false); else SEL_BODY(false, true);
.LBB0_1196:
	s_add_i32 s8, s28, -1
	s_cmp_ge_i32 s8, s23
	s_cbranch_scc1 .LBB0_1222
	s_waitcnt lgkmcnt(0)
	s_and_b32 s29, s99, 0xffff
	s_lshr_b32 s8, s99, 16
	s_and_b32 s9, s8, 0xff
	s_cmp_eq_u32 s9, 0
	s_cbranch_scc1 .LBB0_1222
	s_cmp_ge_i32 s29, s22
	s_cbranch_scc1 .Lmy_orig_1
	s_and_b32 s9, s8, 15
	s_and_b32 s10, s8, 0xf0
	s_cmp_lg_u32 s9, 0
	s_cselect_b32 s11, 1, 0
	s_cmp_lg_u32 s10, 0
	s_cselect_b32 s12, 1, 0
	s_add_i32 s13, s11, s12
	s_cmp_eq_u32 s13, 2
	s_cbranch_scc1 .Lmy_fb_1
	s_cmp_eq_u32 s11, 1
	s_cbranch_scc0 .Lmy_f1_1
	v_add3_u32 v228, s27, v199, v198
	v_add3_u32 v229, s27, v197, v198
	ds_read_b128 v[66:69], v228 offset:16384
	ds_read_b128 v[70:73], v229 offset:16384
	ds_read_b128 v[74:77], v228 offset:18432
	ds_read_b128 v[78:81], v229 offset:18432
	ds_read_b128 v[82:85], v228 offset:20480
	ds_read_b128 v[86:89], v229 offset:20480
	ds_read_b128 v[90:93], v228 offset:22528
	ds_read_b128 v[94:97], v229 offset:22528
	v_and_b32_e32 v239, s8, v206
	v_cmp_ne_u32_e64 s[10:11], 0, v239
	v_cmp_eq_f32_e64 s[12:13], s3, v213
	v_add_u32_e32 v234, s27, v200
	v_add3_u32 v235, v234, v201, v209
	v_add3_u32 v236, v234, v202, v209
	v_cndmask_b32_e64 v230, v213, 0, s[12:13]
	v_sub_f32_e32 v230, v175, v230
	v_add3_u32 v237, v234, v203, v209
	v_add3_u32 v238, v234, v204, v209
	v_cndmask_b32_e64 v230, v173, v230, s[10:11]
	v_mov_b32_e32 v231, v230
	v_mov_b32_e32 v232, v230
	v_mov_b32_e32 v233, v230
	s_and_b64 s[12:13], s[10:11], s[12:13]
	s_waitcnt lgkmcnt(0)
	v_mfma_f32_16x16x32_bf16 v[66:69], v[66:69], v[2:5], v[230:233]
	v_mfma_f32_16x16x32_bf16 v[74:77], v[74:77], v[2:5], v[230:233]
	v_mfma_f32_16x16x32_bf16 v[82:85], v[82:85], v[2:5], v[230:233]
	v_mfma_f32_16x16x32_bf16 v[90:93], v[90:93], v[2:5], v[230:233]
	v_mfma_f32_16x16x32_bf16 v[66:69], v[70:73], v[6:9], v[66:69]
	v_mfma_f32_16x16x32_bf16 v[74:77], v[78:81], v[6:9], v[74:77]
	v_mfma_f32_16x16x32_bf16 v[82:85], v[86:89], v[6:9], v[82:85]
	v_mfma_f32_16x16x32_bf16 v[90:93], v[94:97], v[6:9], v[90:93]
	ds_read_b64_tr_b16 v[98:99], v235 offset:24576
	ds_read_b64_tr_b16 v[100:101], v235 offset:26624
	ds_read_b64_tr_b16 v[102:103], v235 offset:28672
	ds_read_b64_tr_b16 v[104:105], v235 offset:30720
	ds_read_b64_tr_b16 v[106:107], v236 offset:24576
	ds_read_b64_tr_b16 v[108:109], v236 offset:26624
	ds_read_b64_tr_b16 v[110:111], v236 offset:28672
	ds_read_b64_tr_b16 v[112:113], v236 offset:30720
	ds_read_b64_tr_b16 v[114:115], v237 offset:24576
	ds_read_b64_tr_b16 v[116:117], v237 offset:26624
	ds_read_b64_tr_b16 v[118:119], v237 offset:28672
	ds_read_b64_tr_b16 v[120:121], v237 offset:30720
	ds_read_b64_tr_b16 v[122:123], v238 offset:24576
	ds_read_b64_tr_b16 v[124:125], v238 offset:26624
	ds_read_b64_tr_b16 v[126:127], v238 offset:28672
	ds_read_b64_tr_b16 v[128:129], v238 offset:30720
	v_max3_f32 v239, v66, v67, v68
	v_max3_f32 v240, v69, v74, v75
	v_max3_f32 v241, v76, v77, v82
	v_max3_f32 v242, v83, v84, v85
	v_max3_f32 v239, v239, v240, v90
	v_max3_f32 v241, v241, v242, v91
	v_max3_f32 v239, v239, v92, v93
	v_max_f32_e32 v239, v239, v241
	v_cmp_lt_f32_e32 vcc, s96, v239
	s_or_b64 s[12:13], s[12:13], vcc
	s_cmp_lg_u64 s[12:13], 0
	s_cbranch_scc1 .Lmy_slow_0_1
	v_exp_f32_e32 v66, v66
	v_exp_f32_e32 v67, v67
	v_exp_f32_e32 v68, v68
	v_exp_f32_e32 v69, v69
	v_exp_f32_e32 v74, v74
	v_exp_f32_e32 v75, v75
	v_exp_f32_e32 v76, v76
	v_exp_f32_e32 v77, v77
	v_exp_f32_e32 v82, v82
	v_exp_f32_e32 v83, v83
	v_exp_f32_e32 v84, v84
	v_exp_f32_e32 v85, v85
	v_exp_f32_e32 v90, v90
	v_exp_f32_e32 v91, v91
	v_exp_f32_e32 v92, v92
	v_exp_f32_e32 v93, v93
	v_cvt_pk_bf16_f32 v130, v66, v67
	v_cvt_pk_bf16_f32 v131, v68, v69
	v_cvt_pk_bf16_f32 v132, v74, v75
	v_cvt_pk_bf16_f32 v133, v76, v77
	v_cvt_pk_bf16_f32 v134, v82, v83
	v_cvt_pk_bf16_f32 v135, v84, v85
	v_cvt_pk_bf16_f32 v136, v90, v91
	v_cvt_pk_bf16_f32 v137, v92, v93
	s_nop 1
	s_waitcnt lgkmcnt(12)
	v_mfma_f32_16x16x32_bf16 v[62:65], v[98:101], v[130:133], v[62:65]
	v_mfma_f32_16x16x32_bf16 v[58:61], v[22:25], v[130:133], v[58:61]
	v_mfma_f32_16x16x32_bf16 v[62:65], v[102:105], v[134:137], v[62:65]
	s_waitcnt lgkmcnt(8)
	v_mfma_f32_16x16x32_bf16 v[54:57], v[106:109], v[130:133], v[54:57]
	v_mfma_f32_16x16x32_bf16 v[54:57], v[110:113], v[134:137], v[54:57]
	s_waitcnt lgkmcnt(4)
	v_mfma_f32_16x16x32_bf16 v[50:53], v[114:117], v[130:133], v[50:53]
	v_mfma_f32_16x16x32_bf16 v[58:61], v[22:25], v[134:137], v[58:61]
	v_mfma_f32_16x16x32_bf16 v[50:53], v[118:121], v[134:137], v[50:53]
	s_waitcnt lgkmcnt(0)
	v_mfma_f32_16x16x32_bf16 v[46:49], v[122:125], v[130:133], v[46:49]
	v_mfma_f32_16x16x32_bf16 v[46:49], v[126:129], v[134:137], v[46:49]
	s_nop 7
	s_branch .LBB0_1222

; #define NEG_INF (-__builtin_inff())
; DEV unsigned cvtpk(float lo, float hi) { typedef float f2 __attribute__((ext_vector_type(2))); typedef __bf16 b2 __attribute__((ext_vector_type(2))); f2 v = {lo, hi}; b2 b = __builtin_convertvector(v, b2); return __builtin_bit_cast(unsigned, b); }
; DEV void ref_step(f32x4 (&s)[4], float& m, f32x4 (&O)[4], f32x4& L, ab8 (&pf)[2], bool colact) {
;     float mx = fmaxf(fmaxf(s[0][0], s[0][1]), fmaxf(s[0][2], s[0][3]));
; #pragma unroll
;     for (int kt = 1; kt < 4; ++kt) mx = fmaxf(mx, fmaxf(fmaxf(s[kt][0], s[kt][1]), fmaxf(s[kt][2], s[kt][3])));
;     const bool slow = (colact && m == NEG_INF) || mx > 64.f;
;     if (__any(slow)) {
;         mx = fmaxf(mx, __shfl_xor(mx, 16)); mx = fmaxf(mx, __shfl_xor(mx, 32));
;         const bool un = (m == NEG_INF);
;         const float d = (mx == NEG_INF) ? 0.f : (un ? mx : fmaxf(mx, 0.f));
;         const float sc = un ? 1.f : __builtin_amdgcn_exp2f(-d);
; #pragma unroll
;         for (int kt = 0; kt < 4; ++kt) s[kt] = s[kt] - d;
; #pragma unroll
;         for (int dt = 0; dt < 4; ++dt) O[dt] = O[dt] * sc;
;         L = L * sc;
;         m = un ? ((mx == NEG_INF) ? NEG_INF : mx) : m + d;
;     }
; #pragma unroll
;     for (int kt = 0; kt < 4; ++kt)
; #pragma unroll
;         for (int i = 0; i < 4; ++i) s[kt][i] = __builtin_amdgcn_exp2f(s[kt][i]);
; #pragma unroll
;     for (int j = 0; j < 2; ++j) { v4u w; w.x = cvtpk(s[2 * j][0], s[2 * j][1]); w.y = cvtpk(s[2 * j][2], s[2 * j][3]); w.z = cvtpk(s[2 * j + 1][0], s[2 * j + 1][1]); w.w = cvtpk(s[2 * j + 1][2], s[2 * j + 1][3]); pf[j] = __builtin_bit_cast(ab8, w); }
; }
; DEV void attn_unit_mfma(Frame& F, int qg, int kv) {
;     ...
;         const int j = lst[1 + i]; const unsigned byte = (msk[2 * j + (w >> 2)] >> (8 * (w & 3))) & 0xffu;
;         const bool a0 = (byte & 0xfu) != 0u, a1 = (byte & 0xf0u) != 0u;
;         if (a0 || a1) {
;             const bool near = j >= cur - 2; const float bi = near ? 0.f : C.b31;
;             const bool c0 = ((byte >> (C.n >> 2)) & 1u) != 0u, c1 = ((byte >> (4 + (C.n >> 2))) & 1u) != 0u;
;     ...
;             if (a0 && a1) SEL_BODY(true, true); else if (a0) SEL_BODY(true, false); else SEL_BODY(false, true);
.Lmy_f1_1:
	v_add3_u32 v228, s27, v199, v198
	v_add3_u32 v229, s27, v197, v198
	ds_read_b128 v[66:69], v228 offset:16384
	ds_read_b128 v[70:73], v229 offset:16384
	ds_read_b128 v[74:77], v228 offset:18432
	ds_read_b128 v[78:81], v229 offset:18432
	ds_read_b128 v[82:85], v228 offset:20480
	ds_read_b128 v[86:89], v229 offset:20480
	ds_read_b128 v[90:93], v228 offset:22528
	ds_read_b128 v[94:97], v229 offset:22528
	v_and_b32_e32 v239, s8, v207
	v_cmp_ne_u32_e64 s[10:11], 0, v239
	v_cmp_eq_f32_e64 s[12:13], s3, v212
	v_add_u32_e32 v234, s27, v200
	v_add3_u32 v235, v234, v201, v209
	v_add3_u32 v236, v234, v202, v209
	v_cndmask_b32_e64 v230, v212, 0, s[12:13]
	v_sub_f32_e32 v230, v175, v230
	v_add3_u32 v237, v234, v203, v209
	v_add3_u32 v238, v234, v204, v209
	v_cndmask_b32_e64 v230, v173, v230, s[10:11]
	v_mov_b32_e32 v231, v230
	v_mov_b32_e32 v232, v230
	v_mov_b32_e32 v233, v230
	s_and_b64 s[12:13], s[10:11], s[12:13]
	s_waitcnt lgkmcnt(0)
	v_mfma_f32_16x16x32_bf16 v[66:69], v[66:69], v[10:13], v[230:233]
	v_mfma_f32_16x16x32_bf16 v[74:77], v[74:77], v[10:13], v[230:233]
	v_mfma_f32_16x16x32_bf16 v[82:85], v[82:85], v[10:13], v[230:233]
	v_mfma_f32_16x16x32_bf16 v[90:93], v[90:93], v[10:13], v[230:233]
	v_mfma_f32_16x16x32_bf16 v[66:69], v[70:73], v[14:17], v[66:69]
	v_mfma_f32_16x16x32_bf16 v[74:77], v[78:81], v[14:17], v[74:77]
	v_mfma_f32_16x16x32_bf16 v[82:85], v[86:89], v[14:17], v[82:85]
	v_mfma_f32_16x16x32_bf16 v[90:93], v[94:97], v[14:17], v[90:93]
	ds_read_b64_tr_b16 v[98:99], v235 offset:24576
	ds_read_b64_tr_b16 v[100:101], v235 offset:26624
	ds_read_b64_tr_b16 v[102:103], v235 offset:28672
	ds_read_b64_tr_b16 v[104:105], v235 offset:30720
	ds_read_b64_tr_b16 v[106:107], v236 offset:24576
	ds_read_b64_tr_b16 v[108:109], v236 offset:26624
	ds_read_b64_tr_b16 v[110:111], v236 offset:28672
	ds_read_b64_tr_b16 v[112:113], v236 offset:30720
	ds_read_b64_tr_b16 v[114:115], v237 offset:24576
	ds_read_b64_tr_b16 v[116:117], v237 offset:26624
	ds_read_b64_tr_b16 v[118:119], v237 offset:28672
	ds_read_b64_tr_b16 v[120:121], v237 offset:30720
	ds_read_b64_tr_b16 v[122:123], v238 offset:24576
	ds_read_b64_tr_b16 v[124:125], v238 offset:26624
	ds_read_b64_tr_b16 v[126:127], v238 offset:28672
	ds_read_b64_tr_b16 v[128:129], v238 offset:30720
	v_max3_f32 v239, v66, v67, v68
	v_max3_f32 v240, v69, v74, v75
	v_max3_f32 v241, v76, v77, v82
	v_max3_f32 v242, v83, v84, v85
	v_max3_f32 v239, v239, v240, v90
	v_max3_f32 v241, v241, v242, v91
	v_max3_f32 v239, v239, v92, v93
	v_max_f32_e32 v239, v239, v241
	v_cmp_lt_f32_e32 vcc, s96, v239
	s_or_b64 s[12:13], s[12:13], vcc
	s_cmp_lg_u64 s[12:13], 0
	s_cbranch_scc1 .Lmy_slow_1_1
	v_exp_f32_e32 v66, v66
	v_exp_f32_e32 v67, v67
	v_exp_f32_e32 v68, v68
	v_exp_f32_e32 v69, v69
	v_exp_f32_e32 v74, v74
	v_exp_f32_e32 v75, v75
	v_exp_f32_e32 v76, v76
	v_exp_f32_e32 v77, v77
	v_exp_f32_e32 v82, v82
	v_exp_f32_e32 v83, v83
	v_exp_f32_e32 v84, v84
	v_exp_f32_e32 v85, v85
	v_exp_f32_e32 v90, v90
	v_exp_f32_e32 v91, v91
	v_exp_f32_e32 v92, v92
	v_exp_f32_e32 v93, v93
	v_cvt_pk_bf16_f32 v130, v66, v67
	v_cvt_pk_bf16_f32 v131, v68, v69
	v_cvt_pk_bf16_f32 v132, v74, v75
	v_cvt_pk_bf16_f32 v133, v76, v77
	v_cvt_pk_bf16_f32 v134, v82, v83
	v_cvt_pk_bf16_f32 v135, v84, v85
	v_cvt_pk_bf16_f32 v136, v90, v91
	v_cvt_pk_bf16_f32 v137, v92, v93
	s_nop 1
	s_waitcnt lgkmcnt(12)
	v_mfma_f32_16x16x32_bf16 v[38:41], v[98:101], v[130:133], v[38:41]
	v_mfma_f32_16x16x32_bf16 v[42:45], v[22:25], v[130:133], v[42:45]
	v_mfma_f32_16x16x32_bf16 v[38:41], v[102:105], v[134:137], v[38:41]
	s_waitcnt lgkmcnt(8)
	v_mfma_f32_16x16x32_bf16 v[34:37], v[106:109], v[130:133], v[34:37]
	v_mfma_f32_16x16x32_bf16 v[34:37], v[110:113], v[134:137], v[34:37]
	s_waitcnt lgkmcnt(4)
	v_mfma_f32_16x16x32_bf16 v[30:33], v[114:117], v[130:133], v[30:33]
	v_mfma_f32_16x16x32_bf16 v[42:45], v[22:25], v[134:137], v[42:45]
	v_mfma_f32_16x16x32_bf16 v[30:33], v[118:121], v[134:137], v[30:33]
	s_waitcnt lgkmcnt(0)
	v_mfma_f32_16x16x32_bf16 v[26:29], v[122:125], v[130:133], v[26:29]
	v_mfma_f32_16x16x32_bf16 v[26:29], v[126:129], v[134:137], v[26:29]
	s_nop 7
	s_branch .LBB0_1222

; #define NEG_INF (-__builtin_inff())
; DEV void qk64(const LAS unsigned char* Kb, const AttnCtx& C, const ab8 (&qf)[2][2], f32x4 (&s)[2][4], float init0, float init1, bool a0, bool a1) {
;     ab8 k0[4], k1[4];
; #pragma unroll
;     for (int kt = 0; kt < 4; ++kt) { k0[kt] = *(const LAS ab8*)(Kb + swz(16 * kt + C.n, C.q4)); k1[kt] = *(const LAS ab8*)(Kb + swz(16 * kt + C.n, 4 + C.q4)); }
;     __builtin_amdgcn_sched_barrier(0);
; #pragma unroll
;     for (int kt = 0; kt < 4; ++kt) {
;         if (a0) { f32x4 c = {init0, init0, init0, init0}; c = __builtin_amdgcn_mfma_f32_16x16x32_bf16(k0[kt], qf[0][0], c, 0, 0, 0); s[0][kt] = __builtin_amdgcn_mfma_f32_16x16x32_bf16(k1[kt], qf[0][1], c, 0, 0, 0); }
;         if (a1) { f32x4 c = {init1, init1, init1, init1}; c = __builtin_amdgcn_mfma_f32_16x16x32_bf16(k0[kt], qf[1][0], c, 0, 0, 0); s[1][kt] = __builtin_amdgcn_mfma_f32_16x16x32_bf16(k1[kt], qf[1][1], c, 0, 0, 0); }
;     }
; }
; template <bool LUTB, bool WINLO>
; DEV void mask_bias(f32x4 (&s)[4], const AttnCtx& C, int t, int p0, int pstep, bool colok) {
; #pragma unroll
;     for (int kt = 0; kt < 4; ++kt)
; #pragma unroll
;         for (int i = 0; i < 4; ++i) { const int rel = t - (p0 + pstep * (16 * kt + 4 * C.q4 + i));
;             bool ok = colok && rel >= 0; if (WINLO) ok = ok && rel < 512;
;             float v = s[kt][i]; if (LUTB) v += C.lut[C.h * 129 + (rel < 0 ? 0 : (rel < 128 ? rel : 128))];
;             s[kt][i] = ok ? v : NEG_INF; }
; }
; DEV float colmax16(const f32x4 (&s)[4]) {
;     float mx = fmaxf(fmaxf(s[0][0], s[0][1]), fmaxf(s[0][2], s[0][3]));
; #pragma unroll
;     for (int kt = 1; kt < 4; ++kt) mx = fmaxf(mx, fmaxf(fmaxf(s[kt][0], s[kt][1]), fmaxf(s[kt][2], s[kt][3])));
;     mx = fmaxf(mx, __shfl_xor(mx, 16)); mx = fmaxf(mx, __shfl_xor(mx, 32));
;     return mx;
; }
; DEV void attn_unit_mfma(Frame& F, int qg, int kv) {
;     ...
;         const int j = lst[1 + i]; const unsigned byte = (msk[2 * j + (w >> 2)] >> (8 * (w & 3))) & 0xffu;
;         const bool a0 = (byte & 0xfu) != 0u, a1 = (byte & 0xf0u) != 0u;
;         if (a0 || a1) {
;             const bool near = j >= cur - 2; const float bi = near ? 0.f : C.b31;
;             const bool c0 = ((byte >> (C.n >> 2)) & 1u) != 0u, c1 = ((byte >> (4 + (C.n >> 2))) & 1u) != 0u;
;     ...
;             if (a0 && a1) SEL_BODY(true, true); else if (a0) SEL_BODY(true, false); else SEL_BODY(false, true);
.Lmy_fb_1:
	v_add3_u32 v236, s27, v199, v198
	v_add3_u32 v237, s27, v197, v198
	ds_read_b128 v[66:69], v236 offset:16384
	ds_read_b128 v[70:73], v237 offset:16384
	ds_read_b128 v[74:77], v236 offset:18432
	ds_read_b128 v[78:81], v237 offset:18432
	ds_read_b128 v[82:85], v236 offset:20480
	ds_read_b128 v[86:89], v237 offset:20480
	ds_read_b128 v[90:93], v236 offset:22528
	ds_read_b128 v[94:97], v237 offset:22528
	v_and_b32_e32 v243, s8, v206
	v_and_b32_e32 v244, s8, v207
	v_cmp_ne_u32_e64 s[10:11], 0, v243
	v_cmp_ne_u32_e64 s[14:15], 0, v244
	v_cmp_eq_f32_e64 s[12:13], s3, v213
	v_cmp_eq_f32_e64 s[16:17], s3, v212
	v_add_u32_e32 v238, s27, v200
	v_add3_u32 v239, v238, v201, v209
	v_add3_u32 v240, v238, v202, v209
	v_cndmask_b32_e64 v228, v213, 0, s[12:13]
	v_cndmask_b32_e64 v232, v212, 0, s[16:17]
	v_sub_f32_e32 v228, v175, v228
	v_sub_f32_e32 v232, v175, v232
	v_add3_u32 v241, v238, v203, v209
	v_add3_u32 v242, v238, v204, v209
	v_cndmask_b32_e64 v228, v173, v228, s[10:11]
	v_cndmask_b32_e64 v232, v173, v232, s[14:15]
	v_mov_b32_e32 v229, v228
	v_mov_b32_e32 v230, v228
	v_mov_b32_e32 v231, v228
	v_mov_b32_e32 v233, v232
	v_mov_b32_e32 v234, v232
	v_mov_b32_e32 v235, v232
	s_and_b64 s[12:13], s[10:11], s[12:13]
	s_and_b64 s[16:17], s[14:15], s[16:17]
	s_or_b64 s[12:13], s[12:13], s[16:17]
	s_waitcnt lgkmcnt(0)
	v_mfma_f32_16x16x32_bf16 v[98:101], v[66:69], v[10:13], v[232:235]
	v_mfma_f32_16x16x32_bf16 v[102:105], v[74:77], v[10:13], v[232:235]
	v_mfma_f32_16x16x32_bf16 v[106:109], v[82:85], v[10:13], v[232:235]
	v_mfma_f32_16x16x32_bf16 v[110:113], v[90:93], v[10:13], v[232:235]
	v_mfma_f32_16x16x32_bf16 v[66:69], v[66:69], v[2:5], v[228:231]
	v_mfma_f32_16x16x32_bf16 v[74:77], v[74:77], v[2:5], v[228:231]
	v_mfma_f32_16x16x32_bf16 v[82:85], v[82:85], v[2:5], v[228:231]
	v_mfma_f32_16x16x32_bf16 v[90:93], v[90:93], v[2:5], v[228:231]
	v_mfma_f32_16x16x32_bf16 v[66:69], v[70:73], v[6:9], v[66:69]
	v_mfma_f32_16x16x32_bf16 v[74:77], v[78:81], v[6:9], v[74:77]
	v_mfma_f32_16x16x32_bf16 v[82:85], v[86:89], v[6:9], v[82:85]
	v_mfma_f32_16x16x32_bf16 v[90:93], v[94:97], v[6:9], v[90:93]
	v_mfma_f32_16x16x32_bf16 v[70:73], v[70:73], v[14:17], v[98:101]
	v_mfma_f32_16x16x32_bf16 v[78:81], v[78:81], v[14:17], v[102:105]
	v_mfma_f32_16x16x32_bf16 v[86:89], v[86:89], v[14:17], v[106:109]
	v_mfma_f32_16x16x32_bf16 v[94:97], v[94:97], v[14:17], v[110:113]
	ds_read_b64_tr_b16 v[114:115], v241 offset:24576
	ds_read_b64_tr_b16 v[116:117], v241 offset:26624
	ds_read_b64_tr_b16 v[118:119], v241 offset:28672
	ds_read_b64_tr_b16 v[120:121], v241 offset:30720
	ds_read_b64_tr_b16 v[122:123], v242 offset:24576
	ds_read_b64_tr_b16 v[124:125], v242 offset:26624
	ds_read_b64_tr_b16 v[126:127], v242 offset:28672
	ds_read_b64_tr_b16 v[128:129], v242 offset:30720
	ds_read_b64_tr_b16 v[98:99], v239 offset:24576
	ds_read_b64_tr_b16 v[100:101], v239 offset:26624
	ds_read_b64_tr_b16 v[102:103], v239 offset:28672
	ds_read_b64_tr_b16 v[104:105], v239 offset:30720
	ds_read_b64_tr_b16 v[106:107], v240 offset:24576
	ds_read_b64_tr_b16 v[108:109], v240 offset:26624
	ds_read_b64_tr_b16 v[110:111], v240 offset:28672
	ds_read_b64_tr_b16 v[112:113], v240 offset:30720
	v_max3_f32 v243, v66, v67, v68
	v_max3_f32 v244, v69, v74, v75
	v_max3_f32 v245, v76, v77, v82
	v_max3_f32 v246, v83, v84, v85
	v_max3_f32 v243, v243, v244, v90
	v_max3_f32 v245, v245, v246, v91
	v_max3_f32 v243, v243, v92, v93
	v_max_f32_e32 v243, v243, v245
	v_cmp_lt_f32_e32 vcc, s96, v243
	s_or_b64 s[12:13], s[12:13], vcc
	v_max3_f32 v243, v70, v71, v72
	v_max3_f32 v244, v73, v78, v79
	v_max3_f32 v245, v80, v81, v86
	v_max3_f32 v246, v87, v88, v89
	v_max3_f32 v243, v243, v244, v94
	v_max3_f32 v245, v245, v246, v95
	v_max3_f32 v243, v243, v96, v97
	v_max_f32_e32 v243, v243, v245
	v_cmp_lt_f32_e32 vcc, s96, v243
	s_or_b64 s[12:13], s[12:13], vcc
	s_cmp_lg_u64 s[12:13], 0
	s_cbranch_scc1 .Lmy_slow_b_1
	v_exp_f32_e32 v66, v66
	v_exp_f32_e32 v67, v67
	v_exp_f32_e32 v68, v68
	v_exp_f32_e32 v69, v69
	v_exp_f32_e32 v74, v74
	v_exp_f32_e32 v75, v75
	v_exp_f32_e32 v76, v76
	v_exp_f32_e32 v77, v77
	v_exp_f32_e32 v82, v82
	v_exp_f32_e32 v83, v83
	v_exp_f32_e32 v84, v84
	v_exp_f32_e32 v85, v85
	v_exp_f32_e32 v90, v90
	v_exp_f32_e32 v91, v91
	v_exp_f32_e32 v92, v92
	v_exp_f32_e32 v93, v93
	v_exp_f32_e32 v70, v70
	v_exp_f32_e32 v71, v71
	v_exp_f32_e32 v72, v72
	v_exp_f32_e32 v73, v73
	v_exp_f32_e32 v78, v78
	v_exp_f32_e32 v79, v79
	v_exp_f32_e32 v80, v80
	v_exp_f32_e32 v81, v81
	v_exp_f32_e32 v86, v86
	v_exp_f32_e32 v87, v87
	v_exp_f32_e32 v88, v88
	v_exp_f32_e32 v89, v89
	v_exp_f32_e32 v94, v94
	v_exp_f32_e32 v95, v95
	v_exp_f32_e32 v96, v96
	v_exp_f32_e32 v97, v97
	v_cvt_pk_bf16_f32 v130, v66, v67
	v_cvt_pk_bf16_f32 v131, v68, v69
	v_cvt_pk_bf16_f32 v132, v74, v75
	v_cvt_pk_bf16_f32 v133, v76, v77
	v_cvt_pk_bf16_f32 v134, v82, v83
	v_cvt_pk_bf16_f32 v135, v84, v85
	v_cvt_pk_bf16_f32 v136, v90, v91
	v_cvt_pk_bf16_f32 v137, v92, v93
	v_cvt_pk_bf16_f32 v228, v70, v71
	v_cvt_pk_bf16_f32 v229, v72, v73
	v_cvt_pk_bf16_f32 v230, v78, v79
	v_cvt_pk_bf16_f32 v231, v80, v81
	v_cvt_pk_bf16_f32 v232, v86, v87
	v_cvt_pk_bf16_f32 v233, v88, v89
	v_cvt_pk_bf16_f32 v234, v94, v95
	v_cvt_pk_bf16_f32 v235, v96, v97
	s_nop 1
	s_waitcnt lgkmcnt(12)
	v_mfma_f32_16x16x32_bf16 v[50:53], v[114:117], v[130:133], v[50:53]
	v_mfma_f32_16x16x32_bf16 v[30:33], v[114:117], v[228:231], v[30:33]
	v_mfma_f32_16x16x32_bf16 v[58:61], v[22:25], v[130:133], v[58:61]
	v_mfma_f32_16x16x32_bf16 v[42:45], v[22:25], v[228:231], v[42:45]
	v_mfma_f32_16x16x32_bf16 v[50:53], v[118:121], v[134:137], v[50:53]
	v_mfma_f32_16x16x32_bf16 v[30:33], v[118:121], v[232:235], v[30:33]
	s_waitcnt lgkmcnt(8)
	v_mfma_f32_16x16x32_bf16 v[46:49], v[122:125], v[130:133], v[46:49]
	v_mfma_f32_16x16x32_bf16 v[26:29], v[122:125], v[228:231], v[26:29]
	v_mfma_f32_16x16x32_bf16 v[46:49], v[126:129], v[134:137], v[46:49]
	v_mfma_f32_16x16x32_bf16 v[26:29], v[126:129], v[232:235], v[26:29]
	s_waitcnt lgkmcnt(4)
	v_mfma_f32_16x16x32_bf16 v[62:65], v[98:101], v[130:133], v[62:65]
	v_mfma_f32_16x16x32_bf16 v[38:41], v[98:101], v[228:231], v[38:41]
	v_mfma_f32_16x16x32_bf16 v[58:61], v[22:25], v[134:137], v[58:61]
	v_mfma_f32_16x16x32_bf16 v[42:45], v[22:25], v[232:235], v[42:45]
	v_mfma_f32_16x16x32_bf16 v[62:65], v[102:105], v[134:137], v[62:65]
	v_mfma_f32_16x16x32_bf16 v[38:41], v[102:105], v[232:235], v[38:41]
	s_waitcnt lgkmcnt(0)
	v_mfma_f32_16x16x32_bf16 v[54:57], v[106:109], v[130:133], v[54:57]
	v_mfma_f32_16x16x32_bf16 v[34:37], v[106:109], v[228:231], v[34:37]
	v_mfma_f32_16x16x32_bf16 v[54:57], v[110:113], v[134:137], v[54:57]
	v_mfma_f32_16x16x32_bf16 v[34:37], v[110:113], v[232:235], v[34:37]
	s_nop 7
	s_branch .LBB0_1222

; #define LAS __attribute__((address_space(3)))
; #define SS_ISSUE(t, slot) do { LAS unsigned char* d_ = lbase + (slot) * 2 * TILEB; const size_t gb_ = (size_t)rowfn(t) * 256 + goff; \
;         __builtin_amdgcn_global_load_lds((const unsigned*)((const char*)Kg + gb_), (LAS unsigned*)d_, 16, 0, 0); \
;         __builtin_amdgcn_global_load_lds((const unsigned*)((const char*)Vg + gb_), (LAS unsigned*)(d_ + TILEB), 16, 0, 0); } while (0)
; template <int NB, class RowFn, class Compute>
; DEV void stream_stages_dma(Frame& F, int n, const bf16* Kg, const bf16* Vg, RowFn rowfn, Compute compute) {
;     ...
;         for (int b = 0; b < NB; ++b) if (i0 + NB + b < n) SS_ISSUE(i0 + NB + b, (st ^ 1) * NB + b);
;         const LAS unsigned char* cur = F.lds + st * NB * 2 * TILEB;
; #pragma unroll
;         for (int b = 0; b < NB; ++b) if (i0 + b < n) compute(i0 + b, cur + b * 2 * TILEB, cur + b * 2 * TILEB + TILEB);
; DEV void attn_unit_mfma(Frame& F, int qg, int kv) {
;     ...
;         const int j = lst[1 + i]; const unsigned byte = (msk[2 * j + (w >> 2)] >> (8 * (w & 3))) & 0xffu;
;         const bool a0 = (byte & 0xfu) != 0u, a1 = (byte & 0xf0u) != 0u;
;         if (a0 || a1) {
;             const bool near = j >= cur - 2; const float bi = near ? 0.f : C.b31;
;             const bool c0 = ((byte >> (C.n >> 2)) & 1u) != 0u, c1 = ((byte >> (4 + (C.n >> 2))) & 1u) != 0u;
;     ...
;             if (a0 && a1) SEL_BODY(true, true); else if (a0) SEL_BODY(true, false); else SEL_BODY(false, true);
.LBB0_1222:
	s_cmp_ge_i32 s28, s23
	s_cbranch_scc1 .LBB0_1248
	s_waitcnt lgkmcnt(0)
	s_and_b32 s28, s100, 0xffff
	s_lshr_b32 s8, s100, 16
	s_and_b32 s9, s8, 0xff
	s_cmp_eq_u32 s9, 0
	s_cbranch_scc1 .LBB0_1248
	s_cmp_ge_i32 s28, s22
	s_cbranch_scc1 .Lmy_orig_2
	s_and_b32 s9, s8, 15
	s_and_b32 s10, s8, 0xf0
	s_cmp_lg_u32 s9, 0
	s_cselect_b32 s11, 1, 0
	s_cmp_lg_u32 s10, 0
	s_cselect_b32 s12, 1, 0
	s_add_i32 s13, s11, s12
	s_cmp_eq_u32 s13, 2
	s_cbranch_scc1 .Lmy_fb_2
	s_cmp_eq_u32 s11, 1
	s_cbranch_scc0 .Lmy_f1_2
	v_add3_u32 v228, s27, v199, v198
	v_add3_u32 v229, s27, v197, v198
	ds_read_b128 v[66:69], v228 offset:32768
	ds_read_b128 v[70:73], v229 offset:32768
	ds_read_b128 v[74:77], v228 offset:34816
	ds_read_b128 v[78:81], v229 offset:34816
	ds_read_b128 v[82:85], v228 offset:36864
	ds_read_b128 v[86:89], v229 offset:36864
	ds_read_b128 v[90:93], v228 offset:38912
	ds_read_b128 v[94:97], v229 offset:38912
	v_and_b32_e32 v239, s8, v206
	v_cmp_ne_u32_e64 s[10:11], 0, v239
	v_cmp_eq_f32_e64 s[12:13], s3, v213
	v_add_u32_e32 v234, s27, v200
	v_add3_u32 v235, v234, v201, v209
	v_add3_u32 v236, v234, v202, v209
	v_cndmask_b32_e64 v230, v213, 0, s[12:13]
	v_sub_f32_e32 v230, v175, v230
	v_add3_u32 v237, v234, v203, v209
	v_add3_u32 v238, v234, v204, v209
	v_cndmask_b32_e64 v230, v173, v230, s[10:11]
	v_mov_b32_e32 v231, v230
	v_mov_b32_e32 v232, v230
	v_mov_b32_e32 v233, v230
	s_and_b64 s[12:13], s[10:11], s[12:13]
	s_waitcnt lgkmcnt(0)
	v_mfma_f32_16x16x32_bf16 v[66:69], v[66:69], v[2:5], v[230:233]
	v_mfma_f32_16x16x32_bf16 v[74:77], v[74:77], v[2:5], v[230:233]
	v_mfma_f32_16x16x32_bf16 v[82:85], v[82:85], v[2:5], v[230:233]
	v_mfma_f32_16x16x32_bf16 v[90:93], v[90:93], v[2:5], v[230:233]
	v_mfma_f32_16x16x32_bf16 v[66:69], v[70:73], v[6:9], v[66:69]
	v_mfma_f32_16x16x32_bf16 v[74:77], v[78:81], v[6:9], v[74:77]
	v_mfma_f32_16x16x32_bf16 v[82:85], v[86:89], v[6:9], v[82:85]
	v_mfma_f32_16x16x32_bf16 v[90:93], v[94:97], v[6:9], v[90:93]
	ds_read_b64_tr_b16 v[98:99], v235 offset:40960
	ds_read_b64_tr_b16 v[100:101], v235 offset:43008
	ds_read_b64_tr_b16 v[102:103], v235 offset:45056
	ds_read_b64_tr_b16 v[104:105], v235 offset:47104
	ds_read_b64_tr_b16 v[106:107], v236 offset:40960
	ds_read_b64_tr_b16 v[108:109], v236 offset:43008
	ds_read_b64_tr_b16 v[110:111], v236 offset:45056
	ds_read_b64_tr_b16 v[112:113], v236 offset:47104
	ds_read_b64_tr_b16 v[114:115], v237 offset:40960
	ds_read_b64_tr_b16 v[116:117], v237 offset:43008
	ds_read_b64_tr_b16 v[118:119], v237 offset:45056
	ds_read_b64_tr_b16 v[120:121], v237 offset:47104
	ds_read_b64_tr_b16 v[122:123], v238 offset:40960
	ds_read_b64_tr_b16 v[124:125], v238 offset:43008
	ds_read_b64_tr_b16 v[126:127], v238 offset:45056
	ds_read_b64_tr_b16 v[128:129], v238 offset:47104
	v_max3_f32 v239, v66, v67, v68
	v_max3_f32 v240, v69, v74, v75
	v_max3_f32 v241, v76, v77, v82
	v_max3_f32 v242, v83, v84, v85
	v_max3_f32 v239, v239, v240, v90
	v_max3_f32 v241, v241, v242, v91
	v_max3_f32 v239, v239, v92, v93
	v_max_f32_e32 v239, v239, v241
	v_cmp_lt_f32_e32 vcc, s96, v239
	s_or_b64 s[12:13], s[12:13], vcc
	s_cmp_lg_u64 s[12:13], 0
	s_cbranch_scc1 .Lmy_slow_0_2
	v_exp_f32_e32 v66, v66
	v_exp_f32_e32 v67, v67
	v_exp_f32_e32 v68, v68
	v_exp_f32_e32 v69, v69
	v_exp_f32_e32 v74, v74
	v_exp_f32_e32 v75, v75
	v_exp_f32_e32 v76, v76
	v_exp_f32_e32 v77, v77
	v_exp_f32_e32 v82, v82
	v_exp_f32_e32 v83, v83
	v_exp_f32_e32 v84, v84
	v_exp_f32_e32 v85, v85
	v_exp_f32_e32 v90, v90
	v_exp_f32_e32 v91, v91
	v_exp_f32_e32 v92, v92
	v_exp_f32_e32 v93, v93
	v_cvt_pk_bf16_f32 v130, v66, v67
	v_cvt_pk_bf16_f32 v131, v68, v69
	v_cvt_pk_bf16_f32 v132, v74, v75
	v_cvt_pk_bf16_f32 v133, v76, v77
	v_cvt_pk_bf16_f32 v134, v82, v83
	v_cvt_pk_bf16_f32 v135, v84, v85
	v_cvt_pk_bf16_f32 v136, v90, v91
	v_cvt_pk_bf16_f32 v137, v92, v93
	s_nop 1
	s_waitcnt lgkmcnt(12)
	v_mfma_f32_16x16x32_bf16 v[62:65], v[98:101], v[130:133], v[62:65]
	v_mfma_f32_16x16x32_bf16 v[58:61], v[22:25], v[130:133], v[58:61]
	v_mfma_f32_16x16x32_bf16 v[62:65], v[102:105], v[134:137], v[62:65]
	s_waitcnt lgkmcnt(8)
	v_mfma_f32_16x16x32_bf16 v[54:57], v[106:109], v[130:133], v[54:57]
	v_mfma_f32_16x16x32_bf16 v[54:57], v[110:113], v[134:137], v[54:57]
	s_waitcnt lgkmcnt(4)
	v_mfma_f32_16x16x32_bf16 v[50:53], v[114:117], v[130:133], v[50:53]
	v_mfma_f32_16x16x32_bf16 v[58:61], v[22:25], v[134:137], v[58:61]
	v_mfma_f32_16x16x32_bf16 v[50:53], v[118:121], v[134:137], v[50:53]
	s_waitcnt lgkmcnt(0)
	v_mfma_f32_16x16x32_bf16 v[46:49], v[122:125], v[130:133], v[46:49]
	v_mfma_f32_16x16x32_bf16 v[46:49], v[126:129], v[134:137], v[46:49]
	s_nop 7
	s_branch .LBB0_1248

; #define NEG_INF (-__builtin_inff())
; DEV unsigned cvtpk(float lo, float hi) { typedef float f2 __attribute__((ext_vector_type(2))); typedef __bf16 b2 __attribute__((ext_vector_type(2))); f2 v = {lo, hi}; b2 b = __builtin_convertvector(v, b2); return __builtin_bit_cast(unsigned, b); }
; DEV void ref_step(f32x4 (&s)[4], float& m, f32x4 (&O)[4], f32x4& L, ab8 (&pf)[2], bool colact) {
;     float mx = fmaxf(fmaxf(s[0][0], s[0][1]), fmaxf(s[0][2], s[0][3]));
; #pragma unroll
;     for (int kt = 1; kt < 4; ++kt) mx = fmaxf(mx, fmaxf(fmaxf(s[kt][0], s[kt][1]), fmaxf(s[kt][2], s[kt][3])));
;     const bool slow = (colact && m == NEG_INF) || mx > 64.f;
;     if (__any(slow)) {
;         mx = fmaxf(mx, __shfl_xor(mx, 16)); mx = fmaxf(mx, __shfl_xor(mx, 32));
;         const bool un = (m == NEG_INF);
;         const float d = (mx == NEG_INF) ? 0.f : (un ? mx : fmaxf(mx, 0.f));
;         const float sc = un ? 1.f : __builtin_amdgcn_exp2f(-d);
; #pragma unroll
;         for (int kt = 0; kt < 4; ++kt) s[kt] = s[kt] - d;
; #pragma unroll
;         for (int dt = 0; dt < 4; ++dt) O[dt] = O[dt] * sc;
;         L = L * sc;
;         m = un ? ((mx == NEG_INF) ? NEG_INF : mx) : m + d;
;     }
; #pragma unroll
;     for (int kt = 0; kt < 4; ++kt)
; #pragma unroll
;         for (int i = 0; i < 4; ++i) s[kt][i] = __builtin_amdgcn_exp2f(s[kt][i]);
; #pragma unroll
;     for (int j = 0; j < 2; ++j) { v4u w; w.x = cvtpk(s[2 * j][0], s[2 * j][1]); w.y = cvtpk(s[2 * j][2], s[2 * j][3]); w.z = cvtpk(s[2 * j + 1][0], s[2 * j + 1][1]); w.w = cvtpk(s[2 * j + 1][2], s[2 * j + 1][3]); pf[j] = __builtin_bit_cast(ab8, w); }
; }
; DEV void attn_unit_mfma(Frame& F, int qg, int kv) {
;     ...
;         const int j = lst[1 + i]; const unsigned byte = (msk[2 * j + (w >> 2)] >> (8 * (w & 3))) & 0xffu;
;         const bool a0 = (byte & 0xfu) != 0u, a1 = (byte & 0xf0u) != 0u;
;         if (a0 || a1) {
;             const bool near = j >= cur - 2; const float bi = near ? 0.f : C.b31;
;             const bool c0 = ((byte >> (C.n >> 2)) & 1u) != 0u, c1 = ((byte >> (4 + (C.n >> 2))) & 1u) != 0u;
;     ...
;             if (a0 && a1) SEL_BODY(true, true); else if (a0) SEL_BODY(true, false); else SEL_BODY(false, true);
.Lmy_f1_2:
	v_add3_u32 v228, s27, v199, v198
	v_add3_u32 v229, s27, v197, v198
	ds_read_b128 v[66:69], v228 offset:32768
	ds_read_b128 v[70:73], v229 offset:32768
	ds_read_b128 v[74:77], v228 offset:34816
	ds_read_b128 v[78:81], v229 offset:34816
	ds_read_b128 v[82:85], v228 offset:36864
	ds_read_b128 v[86:89], v229 offset:36864
	ds_read_b128 v[90:93], v228 offset:38912
	ds_read_b128 v[94:97], v229 offset:38912
	v_and_b32_e32 v239, s8, v207
	v_cmp_ne_u32_e64 s[10:11], 0, v239
	v_cmp_eq_f32_e64 s[12:13], s3, v212
	v_add_u32_e32 v234, s27, v200
	v_add3_u32 v235, v234, v201, v209
	v_add3_u32 v236, v234, v202, v209
	v_cndmask_b32_e64 v230, v212, 0, s[12:13]
	v_sub_f32_e32 v230, v175, v230
	v_add3_u32 v237, v234, v203, v209
	v_add3_u32 v238, v234, v204, v209
	v_cndmask_b32_e64 v230, v173, v230, s[10:11]
	v_mov_b32_e32 v231, v230
	v_mov_b32_e32 v232, v230
	v_mov_b32_e32 v233, v230
	s_and_b64 s[12:13], s[10:11], s[12:13]
	s_waitcnt lgkmcnt(0)
	v_mfma_f32_16x16x32_bf16 v[66:69], v[66:69], v[10:13], v[230:233]
	v_mfma_f32_16x16x32_bf16 v[74:77], v[74:77], v[10:13], v[230:233]
	v_mfma_f32_16x16x32_bf16 v[82:85], v[82:85], v[10:13], v[230:233]
	v_mfma_f32_16x16x32_bf16 v[90:93], v[90:93], v[10:13], v[230:233]
	v_mfma_f32_16x16x32_bf16 v[66:69], v[70:73], v[14:17], v[66:69]
	v_mfma_f32_16x16x32_bf16 v[74:77], v[78:81], v[14:17], v[74:77]
	v_mfma_f32_16x16x32_bf16 v[82:85], v[86:89], v[14:17], v[82:85]
	v_mfma_f32_16x16x32_bf16 v[90:93], v[94:97], v[14:17], v[90:93]
	ds_read_b64_tr_b16 v[98:99], v235 offset:40960
	ds_read_b64_tr_b16 v[100:101], v235 offset:43008
	ds_read_b64_tr_b16 v[102:103], v235 offset:45056
	ds_read_b64_tr_b16 v[104:105], v235 offset:47104
	ds_read_b64_tr_b16 v[106:107], v236 offset:40960
	ds_read_b64_tr_b16 v[108:109], v236 offset:43008
	ds_read_b64_tr_b16 v[110:111], v236 offset:45056
	ds_read_b64_tr_b16 v[112:113], v236 offset:47104
	ds_read_b64_tr_b16 v[114:115], v237 offset:40960
	ds_read_b64_tr_b16 v[116:117], v237 offset:43008
	ds_read_b64_tr_b16 v[118:119], v237 offset:45056
	ds_read_b64_tr_b16 v[120:121], v237 offset:47104
	ds_read_b64_tr_b16 v[122:123], v238 offset:40960
	ds_read_b64_tr_b16 v[124:125], v238 offset:43008
	ds_read_b64_tr_b16 v[126:127], v238 offset:45056
	ds_read_b64_tr_b16 v[128:129], v238 offset:47104
	v_max3_f32 v239, v66, v67, v68
	v_max3_f32 v240, v69, v74, v75
	v_max3_f32 v241, v76, v77, v82
	v_max3_f32 v242, v83, v84, v85
	v_max3_f32 v239, v239, v240, v90
	v_max3_f32 v241, v241, v242, v91
	v_max3_f32 v239, v239, v92, v93
	v_max_f32_e32 v239, v239, v241
	v_cmp_lt_f32_e32 vcc, s96, v239
	s_or_b64 s[12:13], s[12:13], vcc
	s_cmp_lg_u64 s[12:13], 0
	s_cbranch_scc1 .Lmy_slow_1_2
	v_exp_f32_e32 v66, v66
	v_exp_f32_e32 v67, v67
	v_exp_f32_e32 v68, v68
	v_exp_f32_e32 v69, v69
	v_exp_f32_e32 v74, v74
	v_exp_f32_e32 v75, v75
	v_exp_f32_e32 v76, v76
	v_exp_f32_e32 v77, v77
	v_exp_f32_e32 v82, v82
	v_exp_f32_e32 v83, v83
	v_exp_f32_e32 v84, v84
	v_exp_f32_e32 v85, v85
	v_exp_f32_e32 v90, v90
	v_exp_f32_e32 v91, v91
	v_exp_f32_e32 v92, v92
	v_exp_f32_e32 v93, v93
	v_cvt_pk_bf16_f32 v130, v66, v67
	v_cvt_pk_bf16_f32 v131, v68, v69
	v_cvt_pk_bf16_f32 v132, v74, v75
	v_cvt_pk_bf16_f32 v133, v76, v77
	v_cvt_pk_bf16_f32 v134, v82, v83
	v_cvt_pk_bf16_f32 v135, v84, v85
	v_cvt_pk_bf16_f32 v136, v90, v91
	v_cvt_pk_bf16_f32 v137, v92, v93
	s_nop 1
	s_waitcnt lgkmcnt(12)
	v_mfma_f32_16x16x32_bf16 v[38:41], v[98:101], v[130:133], v[38:41]
	v_mfma_f32_16x16x32_bf16 v[42:45], v[22:25], v[130:133], v[42:45]
	v_mfma_f32_16x16x32_bf16 v[38:41], v[102:105], v[134:137], v[38:41]
	s_waitcnt lgkmcnt(8)
	v_mfma_f32_16x16x32_bf16 v[34:37], v[106:109], v[130:133], v[34:37]
	v_mfma_f32_16x16x32_bf16 v[34:37], v[110:113], v[134:137], v[34:37]
	s_waitcnt lgkmcnt(4)
	v_mfma_f32_16x16x32_bf16 v[30:33], v[114:117], v[130:133], v[30:33]
	v_mfma_f32_16x16x32_bf16 v[42:45], v[22:25], v[134:137], v[42:45]
	v_mfma_f32_16x16x32_bf16 v[30:33], v[118:121], v[134:137], v[30:33]
	s_waitcnt lgkmcnt(0)
	v_mfma_f32_16x16x32_bf16 v[26:29], v[122:125], v[130:133], v[26:29]
	v_mfma_f32_16x16x32_bf16 v[26:29], v[126:129], v[134:137], v[26:29]
	s_nop 7
	s_branch .LBB0_1248

; #define NEG_INF (-__builtin_inff())
; DEV void qk64(const LAS unsigned char* Kb, const AttnCtx& C, const ab8 (&qf)[2][2], f32x4 (&s)[2][4], float init0, float init1, bool a0, bool a1) {
;     ab8 k0[4], k1[4];
; #pragma unroll
;     for (int kt = 0; kt < 4; ++kt) { k0[kt] = *(const LAS ab8*)(Kb + swz(16 * kt + C.n, C.q4)); k1[kt] = *(const LAS ab8*)(Kb + swz(16 * kt + C.n, 4 + C.q4)); }
;     __builtin_amdgcn_sched_barrier(0);
; #pragma unroll
;     for (int kt = 0; kt < 4; ++kt) {
;         if (a0) { f32x4 c = {init0, init0, init0, init0}; c = __builtin_amdgcn_mfma_f32_16x16x32_bf16(k0[kt], qf[0][0], c, 0, 0, 0); s[0][kt] = __builtin_amdgcn_mfma_f32_16x16x32_bf16(k1[kt], qf[0][1], c, 0, 0, 0); }
;         if (a1) { f32x4 c = {init1, init1, init1, init1}; c = __builtin_amdgcn_mfma_f32_16x16x32_bf16(k0[kt], qf[1][0], c, 0, 0, 0); s[1][kt] = __builtin_amdgcn_mfma_f32_16x16x32_bf16(k1[kt], qf[1][1], c, 0, 0, 0); }
;     }
; }
; template <bool LUTB, bool WINLO>
; DEV void mask_bias(f32x4 (&s)[4], const AttnCtx& C, int t, int p0, int pstep, bool colok) {
; #pragma unroll
;     for (int kt = 0; kt < 4; ++kt)
; #pragma unroll
;         for (int i = 0; i < 4; ++i) { const int rel = t - (p0 + pstep * (16 * kt + 4 * C.q4 + i));
;             bool ok = colok && rel >= 0; if (WINLO) ok = ok && rel < 512;
;             float v = s[kt][i]; if (LUTB) v += C.lut[C.h * 129 + (rel < 0 ? 0 : (rel < 128 ? rel : 128))];
;             s[kt][i] = ok ? v : NEG_INF; }
; }
; DEV float colmax16(const f32x4 (&s)[4]) {
;     float mx = fmaxf(fmaxf(s[0][0], s[0][1]), fmaxf(s[0][2], s[0][3]));
; #pragma unroll
;     for (int kt = 1; kt < 4; ++kt) mx = fmaxf(mx, fmaxf(fmaxf(s[kt][0], s[kt][1]), fmaxf(s[kt][2], s[kt][3])));
;     mx = fmaxf(mx, __shfl_xor(mx, 16)); mx = fmaxf(mx, __shfl_xor(mx, 32));
;     return mx;
; }
; DEV void attn_unit_mfma(Frame& F, int qg, int kv) {
;     ...
;         const int j = lst[1 + i]; const unsigned byte = (msk[2 * j + (w >> 2)] >> (8 * (w & 3))) & 0xffu;
;         const bool a0 = (byte & 0xfu) != 0u, a1 = (byte & 0xf0u) != 0u;
;         if (a0 || a1) {
;             const bool near = j >= cur - 2; const float bi = near ? 0.f : C.b31;
;             const bool c0 = ((byte >> (C.n >> 2)) & 1u) != 0u, c1 = ((byte >> (4 + (C.n >> 2))) & 1u) != 0u;
;     ...
;             if (a0 && a1) SEL_BODY(true, true); else if (a0) SEL_BODY(true, false); else SEL_BODY(false, true);
.Lmy_fb_2:
	v_add3_u32 v236, s27, v199, v198
	v_add3_u32 v237, s27, v197, v198
	ds_read_b128 v[66:69], v236 offset:32768
	ds_read_b128 v[70:73], v237 offset:32768
	ds_read_b128 v[74:77], v236 offset:34816
	ds_read_b128 v[78:81], v237 offset:34816
	ds_read_b128 v[82:85], v236 offset:36864
	ds_read_b128 v[86:89], v237 offset:36864
	ds_read_b128 v[90:93], v236 offset:38912
	ds_read_b128 v[94:97], v237 offset:38912
	v_and_b32_e32 v243, s8, v206
	v_and_b32_e32 v244, s8, v207
	v_cmp_ne_u32_e64 s[10:11], 0, v243
	v_cmp_ne_u32_e64 s[14:15], 0, v244
	v_cmp_eq_f32_e64 s[12:13], s3, v213
	v_cmp_eq_f32_e64 s[16:17], s3, v212
	v_add_u32_e32 v238, s27, v200
	v_add3_u32 v239, v238, v201, v209
	v_add3_u32 v240, v238, v202, v209
	v_cndmask_b32_e64 v228, v213, 0, s[12:13]
	v_cndmask_b32_e64 v232, v212, 0, s[16:17]
	v_sub_f32_e32 v228, v175, v228
	v_sub_f32_e32 v232, v175, v232
	v_add3_u32 v241, v238, v203, v209
	v_add3_u32 v242, v238, v204, v209
	v_cndmask_b32_e64 v228, v173, v228, s[10:11]
	v_cndmask_b32_e64 v232, v173, v232, s[14:15]
	v_mov_b32_e32 v229, v228
	v_mov_b32_e32 v230, v228
	v_mov_b32_e32 v231, v228
	v_mov_b32_e32 v233, v232
	v_mov_b32_e32 v234, v232
	v_mov_b32_e32 v235, v232
	s_and_b64 s[12:13], s[10:11], s[12:13]
	s_and_b64 s[16:17], s[14:15], s[16:17]
	s_or_b64 s[12:13], s[12:13], s[16:17]
	s_waitcnt lgkmcnt(0)
	v_mfma_f32_16x16x32_bf16 v[98:101], v[66:69], v[10:13], v[232:235]
	v_mfma_f32_16x16x32_bf16 v[102:105], v[74:77], v[10:13], v[232:235]
	v_mfma_f32_16x16x32_bf16 v[106:109], v[82:85], v[10:13], v[232:235]
	v_mfma_f32_16x16x32_bf16 v[110:113], v[90:93], v[10:13], v[232:235]
	v_mfma_f32_16x16x32_bf16 v[66:69], v[66:69], v[2:5], v[228:231]
	v_mfma_f32_16x16x32_bf16 v[74:77], v[74:77], v[2:5], v[228:231]
	v_mfma_f32_16x16x32_bf16 v[82:85], v[82:85], v[2:5], v[228:231]
	v_mfma_f32_16x16x32_bf16 v[90:93], v[90:93], v[2:5], v[228:231]
	v_mfma_f32_16x16x32_bf16 v[66:69], v[70:73], v[6:9], v[66:69]
	v_mfma_f32_16x16x32_bf16 v[74:77], v[78:81], v[6:9], v[74:77]
	v_mfma_f32_16x16x32_bf16 v[82:85], v[86:89], v[6:9], v[82:85]
	v_mfma_f32_16x16x32_bf16 v[90:93], v[94:97], v[6:9], v[90:93]
	v_mfma_f32_16x16x32_bf16 v[70:73], v[70:73], v[14:17], v[98:101]
	v_mfma_f32_16x16x32_bf16 v[78:81], v[78:81], v[14:17], v[102:105]
	v_mfma_f32_16x16x32_bf16 v[86:89], v[86:89], v[14:17], v[106:109]
	v_mfma_f32_16x16x32_bf16 v[94:97], v[94:97], v[14:17], v[110:113]
	ds_read_b64_tr_b16 v[114:115], v241 offset:40960
	ds_read_b64_tr_b16 v[116:117], v241 offset:43008
	ds_read_b64_tr_b16 v[118:119], v241 offset:45056
	ds_read_b64_tr_b16 v[120:121], v241 offset:47104
	ds_read_b64_tr_b16 v[122:123], v242 offset:40960
	ds_read_b64_tr_b16 v[124:125], v242 offset:43008
	ds_read_b64_tr_b16 v[126:127], v242 offset:45056
	ds_read_b64_tr_b16 v[128:129], v242 offset:47104
	ds_read_b64_tr_b16 v[98:99], v239 offset:40960
	ds_read_b64_tr_b16 v[100:101], v239 offset:43008
	ds_read_b64_tr_b16 v[102:103], v239 offset:45056
	ds_read_b64_tr_b16 v[104:105], v239 offset:47104
	ds_read_b64_tr_b16 v[106:107], v240 offset:40960
	ds_read_b64_tr_b16 v[108:109], v240 offset:43008
	ds_read_b64_tr_b16 v[110:111], v240 offset:45056
	ds_read_b64_tr_b16 v[112:113], v240 offset:47104
	v_max3_f32 v243, v66, v67, v68
	v_max3_f32 v244, v69, v74, v75
	v_max3_f32 v245, v76, v77, v82
	v_max3_f32 v246, v83, v84, v85
	v_max3_f32 v243, v243, v244, v90
	v_max3_f32 v245, v245, v246, v91
	v_max3_f32 v243, v243, v92, v93
	v_max_f32_e32 v243, v243, v245
	v_cmp_lt_f32_e32 vcc, s96, v243
	s_or_b64 s[12:13], s[12:13], vcc
	v_max3_f32 v243, v70, v71, v72
	v_max3_f32 v244, v73, v78, v79
	v_max3_f32 v245, v80, v81, v86
	v_max3_f32 v246, v87, v88, v89
	v_max3_f32 v243, v243, v244, v94
	v_max3_f32 v245, v245, v246, v95
	v_max3_f32 v243, v243, v96, v97
	v_max_f32_e32 v243, v243, v245
	v_cmp_lt_f32_e32 vcc, s96, v243
	s_or_b64 s[12:13], s[12:13], vcc
	s_cmp_lg_u64 s[12:13], 0
	s_cbranch_scc1 .Lmy_slow_b_2
	v_exp_f32_e32 v66, v66
	v_exp_f32_e32 v67, v67
	v_exp_f32_e32 v68, v68
	v_exp_f32_e32 v69, v69
	v_exp_f32_e32 v74, v74
	v_exp_f32_e32 v75, v75
	v_exp_f32_e32 v76, v76
	v_exp_f32_e32 v77, v77
	v_exp_f32_e32 v82, v82
	v_exp_f32_e32 v83, v83
	v_exp_f32_e32 v84, v84
	v_exp_f32_e32 v85, v85
	v_exp_f32_e32 v90, v90
	v_exp_f32_e32 v91, v91
	v_exp_f32_e32 v92, v92
	v_exp_f32_e32 v93, v93
	v_exp_f32_e32 v70, v70
	v_exp_f32_e32 v71, v71
	v_exp_f32_e32 v72, v72
	v_exp_f32_e32 v73, v73
	v_exp_f32_e32 v78, v78
	v_exp_f32_e32 v79, v79
	v_exp_f32_e32 v80, v80
	v_exp_f32_e32 v81, v81
	v_exp_f32_e32 v86, v86
	v_exp_f32_e32 v87, v87
	v_exp_f32_e32 v88, v88
	v_exp_f32_e32 v89, v89
	v_exp_f32_e32 v94, v94
	v_exp_f32_e32 v95, v95
	v_exp_f32_e32 v96, v96
	v_exp_f32_e32 v97, v97
	v_cvt_pk_bf16_f32 v130, v66, v67
	v_cvt_pk_bf16_f32 v131, v68, v69
	v_cvt_pk_bf16_f32 v132, v74, v75
	v_cvt_pk_bf16_f32 v133, v76, v77
	v_cvt_pk_bf16_f32 v134, v82, v83
	v_cvt_pk_bf16_f32 v135, v84, v85
	v_cvt_pk_bf16_f32 v136, v90, v91
	v_cvt_pk_bf16_f32 v137, v92, v93
	v_cvt_pk_bf16_f32 v228, v70, v71
	v_cvt_pk_bf16_f32 v229, v72, v73
	v_cvt_pk_bf16_f32 v230, v78, v79
	v_cvt_pk_bf16_f32 v231, v80, v81
	v_cvt_pk_bf16_f32 v232, v86, v87
	v_cvt_pk_bf16_f32 v233, v88, v89
	v_cvt_pk_bf16_f32 v234, v94, v95
	v_cvt_pk_bf16_f32 v235, v96, v97
	s_nop 1
	s_waitcnt lgkmcnt(12)
	v_mfma_f32_16x16x32_bf16 v[50:53], v[114:117], v[130:133], v[50:53]
	v_mfma_f32_16x16x32_bf16 v[30:33], v[114:117], v[228:231], v[30:33]
	v_mfma_f32_16x16x32_bf16 v[58:61], v[22:25], v[130:133], v[58:61]
	v_mfma_f32_16x16x32_bf16 v[42:45], v[22:25], v[228:231], v[42:45]
	v_mfma_f32_16x16x32_bf16 v[50:53], v[118:121], v[134:137], v[50:53]
	v_mfma_f32_16x16x32_bf16 v[30:33], v[118:121], v[232:235], v[30:33]
	s_waitcnt lgkmcnt(8)
	v_mfma_f32_16x16x32_bf16 v[46:49], v[122:125], v[130:133], v[46:49]
	v_mfma_f32_16x16x32_bf16 v[26:29], v[122:125], v[228:231], v[26:29]
	v_mfma_f32_16x16x32_bf16 v[46:49], v[126:129], v[134:137], v[46:49]
	v_mfma_f32_16x16x32_bf16 v[26:29], v[126:129], v[232:235], v[26:29]
	s_waitcnt lgkmcnt(4)
	v_mfma_f32_16x16x32_bf16 v[62:65], v[98:101], v[130:133], v[62:65]
	v_mfma_f32_16x16x32_bf16 v[38:41], v[98:101], v[228:231], v[38:41]
	v_mfma_f32_16x16x32_bf16 v[58:61], v[22:25], v[134:137], v[58:61]
	v_mfma_f32_16x16x32_bf16 v[42:45], v[22:25], v[232:235], v[42:45]
	v_mfma_f32_16x16x32_bf16 v[62:65], v[102:105], v[134:137], v[62:65]
	v_mfma_f32_16x16x32_bf16 v[38:41], v[102:105], v[232:235], v[38:41]
	s_waitcnt lgkmcnt(0)
	v_mfma_f32_16x16x32_bf16 v[54:57], v[106:109], v[130:133], v[54:57]
	v_mfma_f32_16x16x32_bf16 v[34:37], v[106:109], v[228:231], v[34:37]
	v_mfma_f32_16x16x32_bf16 v[54:57], v[110:113], v[134:137], v[54:57]
	v_mfma_f32_16x16x32_bf16 v[34:37], v[110:113], v[232:235], v[34:37]
	s_nop 7
	s_branch .LBB0_1248
